# v14 + P0: pad the LDS gate-weight table (144-byte stride per 4-row group) so the 32 ds_read_b128 per token row are bank-conflict-free (were 8-way conflicts)
# speedup vs baseline: 1.0426x; 1.0268x over previous
.LBB0_19:
	v_lshrrev_b32_e32 v12, 3, v128
	v_lshlrev_b32_e32 v13, 2, v12
	v_mad_u64_u32 v[14:15], s[0:1], v12, s19, v[6:7]
	v_lshl_add_u64 v[14:15], v[14:15], 0, v[2:3]
	s_mov_b64 s[98:99], 0x2000
	v_lshl_add_u64 v[14:15], v[14:15], 0, s[98:99]
	s_mov_b64 s[98:99], 0x100800
	v_add_u32_e32 v16, 0x11000, v1
	v_lshrrev_b32_e32 v17, 5, v128
	v_lshl_add_u32 v16, v17, 4, v16
	global_load_dword v32, v13, s[64:65]
	global_load_dword v48, v[14:15], off
	v_lshl_add_u64 v[14:15], v[14:15], 0, s[98:99]
	global_load_dword v33, v13, s[64:65] offset:256
	global_load_dword v49, v[14:15], off
	v_lshl_add_u64 v[14:15], v[14:15], 0, s[98:99]
	global_load_dword v34, v13, s[64:65] offset:512
	global_load_dword v50, v[14:15], off
	v_lshl_add_u64 v[14:15], v[14:15], 0, s[98:99]
	global_load_dword v35, v13, s[64:65] offset:768
	global_load_dword v51, v[14:15], off
	v_lshl_add_u64 v[14:15], v[14:15], 0, s[98:99]
	global_load_dword v36, v13, s[64:65] offset:1024
	global_load_dword v52, v[14:15], off
	v_lshl_add_u64 v[14:15], v[14:15], 0, s[98:99]
	global_load_dword v37, v13, s[64:65] offset:1280
	global_load_dword v53, v[14:15], off
	v_lshl_add_u64 v[14:15], v[14:15], 0, s[98:99]
	global_load_dword v38, v13, s[64:65] offset:1536
	global_load_dword v54, v[14:15], off
	v_lshl_add_u64 v[14:15], v[14:15], 0, s[98:99]
	global_load_dword v39, v13, s[64:65] offset:1792
	global_load_dword v55, v[14:15], off
	v_lshl_add_u64 v[14:15], v[14:15], 0, s[98:99]
	global_load_dword v40, v13, s[64:65] offset:2048
	global_load_dword v56, v[14:15], off
	v_lshl_add_u64 v[14:15], v[14:15], 0, s[98:99]
	global_load_dword v41, v13, s[64:65] offset:2304
	global_load_dword v57, v[14:15], off
	v_lshl_add_u64 v[14:15], v[14:15], 0, s[98:99]
	global_load_dword v42, v13, s[64:65] offset:2560
	global_load_dword v58, v[14:15], off
	v_lshl_add_u64 v[14:15], v[14:15], 0, s[98:99]
	global_load_dword v43, v13, s[64:65] offset:2816
	global_load_dword v59, v[14:15], off
	v_lshl_add_u64 v[14:15], v[14:15], 0, s[98:99]
	global_load_dword v44, v13, s[64:65] offset:3072
	global_load_dword v60, v[14:15], off
	v_lshl_add_u64 v[14:15], v[14:15], 0, s[98:99]
	global_load_dword v45, v13, s[64:65] offset:3328
	global_load_dword v61, v[14:15], off
	v_lshl_add_u64 v[14:15], v[14:15], 0, s[98:99]
	global_load_dword v46, v13, s[64:65] offset:3584
	global_load_dword v62, v[14:15], off
	v_lshl_add_u64 v[14:15], v[14:15], 0, s[98:99]
	global_load_dword v47, v13, s[64:65] offset:3840
	global_load_dword v63, v[14:15], off
	s_mov_b32 s18, 16
	s_waitcnt vmcnt(0)
	v_mul_f32_e32 v32, v32, v48
	v_mul_f32_e32 v33, v33, v49
	v_mul_f32_e32 v34, v34, v50
	v_mul_f32_e32 v35, v35, v51
	v_mul_f32_e32 v36, v36, v52
	v_mul_f32_e32 v37, v37, v53
	v_mul_f32_e32 v38, v38, v54
	v_mul_f32_e32 v39, v39, v55
	v_mul_f32_e32 v40, v40, v56
	v_mul_f32_e32 v41, v41, v57
	v_mul_f32_e32 v42, v42, v58
	v_mul_f32_e32 v43, v43, v59
	v_mul_f32_e32 v44, v44, v60
	v_mul_f32_e32 v45, v45, v61
	v_mul_f32_e32 v46, v46, v62
	v_mul_f32_e32 v47, v47, v63
	ds_write_b32 v16, v32
	ds_write_b32 v16, v33 offset:2304
	ds_write_b32 v16, v34 offset:4608
	ds_write_b32 v16, v35 offset:6912
	ds_write_b32 v16, v36 offset:9216
	ds_write_b32 v16, v37 offset:11520
	ds_write_b32 v16, v38 offset:13824
	ds_write_b32 v16, v39 offset:16128
	ds_write_b32 v16, v40 offset:18432
	ds_write_b32 v16, v41 offset:20736
	ds_write_b32 v16, v42 offset:23040
	ds_write_b32 v16, v43 offset:25344
	ds_write_b32 v16, v44 offset:27648
	ds_write_b32 v16, v45 offset:29952
	ds_write_b32 v16, v46 offset:32256
	ds_write_b32 v16, v47 offset:34560
	s_or_b64 exec, exec, s[16:17]
	v_and_b32_e32 v3, 2, v10
	v_cmp_eq_u32_e32 vcc, 0, v3
	s_and_saveexec_b64 s[0:1], vcc
	s_cbranch_execz .LBB0_22
	v_lshrrev_b32_e32 v3, 3, v5
	v_lshrrev_b32_e32 v10, 3, v4
	s_movk_i32 s14, 0x4020
	v_mov_b64_e32 v[6:7], s[56:57]
	v_lshlrev_b32_e32 v4, 2, v10
	v_lshlrev_b32_e32 v5, 2, v3
	v_mad_u64_u32 v[10:11], s[16:17], v10, s14, v[6:7]
	v_mad_u64_u32 v[6:7], s[16:17], v3, s14, v[6:7]
	v_mov_b32_e32 v3, 0
	v_lshl_add_u64 v[10:11], v[10:11], 0, v[2:3]
	s_movk_i32 s14, 0x2000
	v_lshl_add_u64 v[2:3], v[6:7], 0, v[2:3]
	v_add_co_u32_e32 v6, vcc, s14, v10
	global_load_dword v4, v4, s[64:65]
	s_nop 0
	global_load_dword v5, v5, s[64:65]
	v_addc_co_u32_e32 v7, vcc, 0, v11, vcc
	v_add_co_u32_e32 v2, vcc, s14, v2
	s_nop 1
	v_addc_co_u32_e32 v3, vcc, 0, v3, vcc
	global_load_dword v6, v[6:7], off
	s_nop 0
	global_load_dword v7, v[2:3], off
	v_lshl_or_b32 v2, v9, 11, v1
	v_add_u32_e32 v9, 0, v2
	s_waitcnt vmcnt(0)
	v_pk_mul_f32 v[2:3], v[4:5], v[6:7]
	v_add_u32_e32 v4, 0x11000, v9
	ds_write2st64_b32 v4, v2, v3 offset1:8

.LBB0_145:
	s_or_b64 exec, exec, s[16:17]
	s_movk_i32 s0, 0xe80
	v_cmp_gt_i32_e32 vcc, s0, v81
	s_and_saveexec_b64 s[0:1], vcc
	v_readlane_b32 s96, v255, 40
	v_readlane_b32 s94, v255, 37
	v_readlane_b32 s82, v255, 35
	v_readlane_b32 s97, v255, 41
	v_readlane_b32 s93, v255, 39
	v_readlane_b32 s95, v255, 38
	v_readlane_b32 s83, v255, 36
	s_cbranch_execz .LBB0_226
	v_mbcnt_lo_u32_b32 v0, -1, 0
	v_mbcnt_hi_u32_b32 v0, -1, v0
	v_and_b32_e32 v1, 64, v0
	v_add_u32_e32 v1, 64, v1
	v_xor_b32_e32 v2, 1, v0
	v_cmp_lt_i32_e32 vcc, v2, v1
	s_add_u32 s56, s28, 0x2300000
	s_addc_u32 s57, s29, 0
	v_cndmask_b32_e32 v2, v0, v2, vcc
	v_lshlrev_b32_e32 v111, 2, v2
	v_xor_b32_e32 v2, 2, v0
	v_cmp_lt_i32_e32 vcc, v2, v1
	s_add_u32 s64, s28, 0x3000000
	s_addc_u32 s65, s29, 0
	v_cndmask_b32_e32 v2, v0, v2, vcc
	v_lshlrev_b32_e32 v112, 2, v2
	v_xor_b32_e32 v2, 4, v0
	v_cmp_lt_i32_e32 vcc, v2, v1
	s_add_i32 s4, 0, 0x11000
	v_lshl_add_u32 v110, v80, 7, s4
	v_lshl_add_u32 v110, v80, 4, v110
	v_cndmask_b32_e32 v2, v0, v2, vcc
	v_lshlrev_b32_e32 v113, 2, v2
	v_xor_b32_e32 v2, 8, v0
	v_cmp_lt_i32_e32 vcc, v2, v1
	s_mul_i32 s4, s22, 40
	s_waitcnt vmcnt(7)
	v_mov_b32_e32 v83, 0
	v_cndmask_b32_e32 v2, v0, v2, vcc
	v_lshlrev_b32_e32 v114, 2, v2
	v_xor_b32_e32 v2, 16, v0
	v_cmp_lt_i32_e32 vcc, v2, v1
	s_waitcnt vmcnt(6)
	v_lshlrev_b32_e32 v84, 4, v80
	v_cmp_eq_u32_e64 s[2:3], 0, v80
	v_cndmask_b32_e32 v2, v0, v2, vcc
	v_lshlrev_b32_e32 v115, 2, v2
	v_xor_b32_e32 v2, 32, v0
	v_cmp_lt_i32_e32 vcc, v2, v1
	s_mul_i32 s68, s34, 40
	s_mov_b64 s[16:17], 0
	v_cndmask_b32_e32 v0, v0, v2, vcc
	v_lshlrev_b32_e32 v116, 2, v0
	v_mad_u32_u24 v0, v58, 5, s4
	v_add_u32_e32 v82, 0xffffbf80, v0
	s_movk_i32 s69, 0xce6
	s_movk_i32 s71, 0xce7
	s_movk_i32 s72, 0xccc
	v_mov_b32_e32 v86, v84
	v_mov_b32_e32 v87, v83
	s_movk_i32 s73, 0xce5
	s_movk_i32 s74, 0xccb
	s_movk_i32 s75, 0x7fff
	v_mov_b32_e32 v117, 0x358637bd
	s_mov_b32 s76, 0x800000
	s_mov_b32 s77, 0x43000
	s_movk_i32 s78, 0xe7f
	v_mov_b32_e32 v118, 1
	s_branch .LBB0_149

.LBB0_185:
	s_or_saveexec_b64 s[18:19], s[18:19]
	v_add_u32_e32 v92, 4, v82
	s_xor_b64 exec, exec, s[18:19]
	v_mov_b32_e32 v93, v83
	v_mov_b64_e32 v[0:1], v[92:93]
	s_or_b64 exec, exec, s[18:19]
	v_lshlrev_b64 v[0:1], 12, v[0:1]
	v_lshl_add_u64 v[0:1], v[2:3], 0, v[0:1]
	v_mov_b32_e32 v85, v83
	v_lshl_add_u64 v[0:1], v[0:1], 0, v[84:85]
	s_waitcnt lgkmcnt(1)
	global_load_dwordx4 v[12:15], v[0:1], off nt
	s_waitcnt lgkmcnt(0)
	global_load_dwordx4 v[8:11], v[0:1], off offset:1024 nt
	global_load_dwordx4 v[4:7], v[0:1], off offset:2048 nt
	s_nop 0
	global_load_dwordx4 v[0:3], v[0:1], off offset:3072 nt
	v_ashrrev_i32_e32 v105, 31, v104
	v_mov_b32_e32 v85, s65
	v_mov_b32_e32 v89, s57
	v_cndmask_b32_e64 v95, v105, 0, s[10:11]
	v_cndmask_b32_e64 v94, v104, v82, s[10:11]
	v_cndmask_b32_e64 v109, v85, v89, s[10:11]
	v_mov_b32_e32 v85, s64
	v_mov_b32_e32 v89, s56
	v_cndmask_b32_e64 v108, v85, v89, s[10:11]
	v_lshlrev_b64 v[94:95], 11, v[94:95]
	s_waitcnt vmcnt(19)
	v_mul_f32_e32 v85, v77, v77
	v_mul_f32_e32 v89, v79, v79
	v_lshl_add_u64 v[120:121], v[108:109], 0, v[94:95]
	v_fmac_f32_e32 v85, v76, v76
	v_fmac_f32_e32 v89, v78, v78
	v_and_b32_sdwa v93, v79, v118 dst_sel:DWORD dst_unused:UNUSED_PAD src0_sel:WORD_1 src1_sel:DWORD
	v_and_b32_sdwa v94, v77, v118 dst_sel:DWORD dst_unused:UNUSED_PAD src0_sel:WORD_1 src1_sel:DWORD
	v_add_f32_e32 v85, v85, v89
	v_and_b32_sdwa v89, v78, v118 dst_sel:DWORD dst_unused:UNUSED_PAD src0_sel:WORD_1 src1_sel:DWORD
	v_and_b32_sdwa v91, v76, v118 dst_sel:DWORD dst_unused:UNUSED_PAD src0_sel:WORD_1 src1_sel:DWORD
	v_add3_u32 v93, v79, v93, s75
	v_add3_u32 v94, v77, v94, s75
	v_add3_u32 v91, v76, v91, s75
	v_add3_u32 v89, v78, v89, s75
	v_and_b32_e32 v93, 0xffff0000, v93
	v_and_b32_e32 v94, 0xffff0000, v94
	v_or_b32_sdwa v123, v93, v89 dst_sel:DWORD dst_unused:UNUSED_PAD src0_sel:DWORD src1_sel:WORD_1
	v_or_b32_sdwa v122, v94, v91 dst_sel:DWORD dst_unused:UNUSED_PAD src0_sel:DWORD src1_sel:WORD_1
	s_waitcnt vmcnt(18)
	v_mul_f32_e32 v89, v73, v73
	v_mul_f32_e32 v91, v75, v75
	v_lshlrev_b32_e32 v94, 3, v80
	v_mov_b32_e32 v95, v83
	v_fmac_f32_e32 v89, v72, v72
	v_fmac_f32_e32 v91, v74, v74
	v_lshl_add_u64 v[120:121], v[120:121], 0, v[94:95]
	v_add_f32_e32 v89, v89, v91
	v_and_b32_sdwa v93, v75, v118 dst_sel:DWORD dst_unused:UNUSED_PAD src0_sel:WORD_1 src1_sel:DWORD
	v_and_b32_sdwa v95, v73, v118 dst_sel:DWORD dst_unused:UNUSED_PAD src0_sel:WORD_1 src1_sel:DWORD
	v_add_f32_e32 v85, v85, v89
	v_and_b32_sdwa v89, v74, v118 dst_sel:DWORD dst_unused:UNUSED_PAD src0_sel:WORD_1 src1_sel:DWORD
	v_and_b32_sdwa v91, v72, v118 dst_sel:DWORD dst_unused:UNUSED_PAD src0_sel:WORD_1 src1_sel:DWORD
	v_add3_u32 v93, v75, v93, s75
	v_add3_u32 v95, v73, v95, s75
	v_add3_u32 v91, v72, v91, s75
	v_add3_u32 v89, v74, v89, s75
	v_and_b32_e32 v93, 0xffff0000, v93
	v_and_b32_e32 v95, 0xffff0000, v95
	global_store_dwordx2 v[120:121], v[122:123], off
	v_or_b32_sdwa v123, v93, v89 dst_sel:DWORD dst_unused:UNUSED_PAD src0_sel:DWORD src1_sel:WORD_1
	v_or_b32_sdwa v122, v95, v91 dst_sel:DWORD dst_unused:UNUSED_PAD src0_sel:DWORD src1_sel:WORD_1
	s_waitcnt vmcnt(18)
	v_mul_f32_e32 v89, v69, v69
	v_mul_f32_e32 v91, v71, v71
	v_fmac_f32_e32 v89, v68, v68
	v_fmac_f32_e32 v91, v70, v70
	s_waitcnt vmcnt(17)
	v_mul_f32_e32 v93, v65, v65
	v_mul_f32_e32 v95, v67, v67
	v_add_f32_e32 v89, v89, v91
	v_fmac_f32_e32 v93, v64, v64
	v_fmac_f32_e32 v95, v66, v66
	v_add_f32_e32 v85, v85, v89
	v_add_f32_e32 v93, v93, v95
	v_add_f32_e32 v85, v85, v93
	ds_bpermute_b32 v93, v111, v85
	v_and_b32_sdwa v97, v69, v118 dst_sel:DWORD dst_unused:UNUSED_PAD src0_sel:WORD_1 src1_sel:DWORD
	v_and_b32_sdwa v91, v68, v118 dst_sel:DWORD dst_unused:UNUSED_PAD src0_sel:WORD_1 src1_sel:DWORD
	v_add3_u32 v97, v69, v97, s75
	v_add3_u32 v91, v68, v91, s75
	s_waitcnt lgkmcnt(0)
	v_add_f32_e32 v85, v85, v93
	ds_bpermute_b32 v93, v112, v85
	v_and_b32_e32 v97, 0xffff0000, v97
	global_store_dwordx2 v[120:121], v[122:123], off offset:512
	v_or_b32_sdwa v122, v97, v91 dst_sel:DWORD dst_unused:UNUSED_PAD src0_sel:DWORD src1_sel:WORD_1
	v_and_b32_sdwa v95, v71, v118 dst_sel:DWORD dst_unused:UNUSED_PAD src0_sel:WORD_1 src1_sel:DWORD
	s_waitcnt lgkmcnt(0)
	v_add_f32_e32 v85, v85, v93
	ds_bpermute_b32 v93, v113, v85
	v_and_b32_sdwa v89, v70, v118 dst_sel:DWORD dst_unused:UNUSED_PAD src0_sel:WORD_1 src1_sel:DWORD
	v_add3_u32 v95, v71, v95, s75
	v_add3_u32 v89, v70, v89, s75
	v_and_b32_e32 v95, 0xffff0000, v95
	s_waitcnt lgkmcnt(0)
	v_add_f32_e32 v85, v85, v93
	ds_bpermute_b32 v91, v114, v85
	v_or_b32_sdwa v123, v95, v89 dst_sel:DWORD dst_unused:UNUSED_PAD src0_sel:DWORD src1_sel:WORD_1
	v_and_b32_sdwa v95, v67, v118 dst_sel:DWORD dst_unused:UNUSED_PAD src0_sel:WORD_1 src1_sel:DWORD
	v_and_b32_sdwa v97, v65, v118 dst_sel:DWORD dst_unused:UNUSED_PAD src0_sel:WORD_1 src1_sel:DWORD
	v_and_b32_sdwa v89, v66, v118 dst_sel:DWORD dst_unused:UNUSED_PAD src0_sel:WORD_1 src1_sel:DWORD
	s_waitcnt lgkmcnt(0)
	v_add_f32_e32 v85, v85, v91
	ds_bpermute_b32 v91, v115, v85
	v_and_b32_sdwa v93, v64, v118 dst_sel:DWORD dst_unused:UNUSED_PAD src0_sel:WORD_1 src1_sel:DWORD
	v_add3_u32 v95, v67, v95, s75
	v_add3_u32 v97, v65, v97, s75
	v_add3_u32 v93, v64, v93, s75
	s_waitcnt lgkmcnt(0)
	v_add_f32_e32 v85, v85, v91
	ds_bpermute_b32 v91, v116, v85
	v_add3_u32 v89, v66, v89, s75
	v_and_b32_e32 v95, 0xffff0000, v95
	v_and_b32_e32 v97, 0xffff0000, v97
	global_store_dwordx2 v[120:121], v[122:123], off offset:1024
	v_or_b32_sdwa v123, v95, v89 dst_sel:DWORD dst_unused:UNUSED_PAD src0_sel:DWORD src1_sel:WORD_1
	v_or_b32_sdwa v122, v97, v93 dst_sel:DWORD dst_unused:UNUSED_PAD src0_sel:DWORD src1_sel:WORD_1
	s_waitcnt lgkmcnt(0)
	v_add_f32_e32 v85, v85, v91
	global_store_dwordx2 v[120:121], v[122:123], off offset:1536
	s_and_saveexec_b64 s[14:15], s[8:9]
	s_xor_b64 s[18:19], exec, s[14:15]
	s_cbranch_execz .LBB0_191
	ds_read_b128 v[120:123], v110
	ds_read_b128 v[124:127], v110 offset:16
	ds_read_b128 v[130:133], v110 offset:32
	ds_read_b128 v[134:137], v110 offset:48
	s_waitcnt lgkmcnt(3)
	v_fma_f32 v89, v76, v120, 0
	v_fma_f32 v91, v76, v121, 0
	v_fma_f32 v93, v76, v122, 0
	v_fma_f32 v95, v76, v123, 0
	s_waitcnt lgkmcnt(2)
	v_fma_f32 v97, v76, v124, 0
	v_fma_f32 v99, v76, v125, 0
	v_fma_f32 v101, v76, v126, 0
	v_fma_f32 v103, v76, v127, 0
	ds_read_b128 v[120:123], v110 offset:64
	ds_read_b128 v[124:127], v110 offset:80
	s_waitcnt lgkmcnt(3)
	v_fmac_f32_e32 v89, v77, v130
	v_fmac_f32_e32 v91, v77, v131
	v_fmac_f32_e32 v93, v77, v132
	v_fmac_f32_e32 v95, v77, v133
	s_waitcnt lgkmcnt(2)
	v_fmac_f32_e32 v97, v77, v134
	v_fmac_f32_e32 v99, v77, v135
	v_fmac_f32_e32 v101, v77, v136
	v_fmac_f32_e32 v103, v77, v137
	s_waitcnt lgkmcnt(1)
	v_fmac_f32_e32 v89, v78, v120
	v_fmac_f32_e32 v91, v78, v121
	v_fmac_f32_e32 v93, v78, v122
	v_fmac_f32_e32 v95, v78, v123
	s_waitcnt lgkmcnt(0)
	v_fmac_f32_e32 v97, v78, v124
	ds_read_b128 v[120:123], v110 offset:96
	v_fmac_f32_e32 v99, v78, v125
	v_fmac_f32_e32 v101, v78, v126
	v_fmac_f32_e32 v103, v78, v127
	ds_read_b128 v[124:127], v110 offset:112
	s_waitcnt lgkmcnt(1)
	v_fmac_f32_e32 v89, v79, v120
	v_fmac_f32_e32 v91, v79, v121
	v_fmac_f32_e32 v93, v79, v122
	v_fmac_f32_e32 v95, v79, v123
	s_waitcnt lgkmcnt(0)
	v_fmac_f32_e32 v97, v79, v124
	ds_read_b128 v[120:123], v110 offset:9216
	v_fmac_f32_e32 v99, v79, v125
	v_fmac_f32_e32 v101, v79, v126
	v_fmac_f32_e32 v103, v79, v127
	ds_read_b128 v[76:79], v110 offset:9232
	s_waitcnt lgkmcnt(1)
	v_fmac_f32_e32 v89, v72, v120
	v_fmac_f32_e32 v91, v72, v121
	v_fmac_f32_e32 v93, v72, v122
	v_fmac_f32_e32 v95, v72, v123
	s_waitcnt lgkmcnt(0)
	v_fmac_f32_e32 v97, v72, v76
	ds_read_b128 v[120:123], v110 offset:9248
	v_fmac_f32_e32 v99, v72, v77
	v_fmac_f32_e32 v101, v72, v78
	v_fmac_f32_e32 v103, v72, v79
	ds_read_b128 v[76:79], v110 offset:9264
	s_waitcnt lgkmcnt(1)
	v_fmac_f32_e32 v89, v73, v120
	v_fmac_f32_e32 v91, v73, v121
	v_fmac_f32_e32 v93, v73, v122
	v_fmac_f32_e32 v95, v73, v123
	s_waitcnt lgkmcnt(0)
	v_fmac_f32_e32 v97, v73, v76
	ds_read_b128 v[120:123], v110 offset:9280
	v_fmac_f32_e32 v99, v73, v77
	v_fmac_f32_e32 v101, v73, v78
	v_fmac_f32_e32 v103, v73, v79
	ds_read_b128 v[76:79], v110 offset:9296
	s_waitcnt lgkmcnt(1)
	v_fmac_f32_e32 v89, v74, v120
	v_fmac_f32_e32 v91, v74, v121
	v_fmac_f32_e32 v93, v74, v122
	v_fmac_f32_e32 v95, v74, v123
	s_waitcnt lgkmcnt(0)
	v_fmac_f32_e32 v97, v74, v76
	ds_read_b128 v[120:123], v110 offset:9312
	v_fmac_f32_e32 v99, v74, v77
	v_fmac_f32_e32 v101, v74, v78
	v_fmac_f32_e32 v103, v74, v79
	ds_read_b128 v[76:79], v110 offset:9328
	s_waitcnt lgkmcnt(1)
	v_fmac_f32_e32 v89, v75, v120
	v_fmac_f32_e32 v91, v75, v121
	v_fmac_f32_e32 v93, v75, v122
	v_fmac_f32_e32 v95, v75, v123
	s_waitcnt lgkmcnt(0)
	v_fmac_f32_e32 v97, v75, v76
	ds_read_b128 v[120:123], v110 offset:18432
	v_fmac_f32_e32 v99, v75, v77
	v_fmac_f32_e32 v101, v75, v78
	v_fmac_f32_e32 v103, v75, v79
	ds_read_b128 v[72:75], v110 offset:18448
	ds_read_b128 v[76:79], v110 offset:18464
	s_waitcnt lgkmcnt(2)
	v_fmac_f32_e32 v89, v68, v120
	v_fmac_f32_e32 v91, v68, v121
	v_fmac_f32_e32 v93, v68, v122
	s_waitcnt lgkmcnt(1)
	v_fmac_f32_e32 v97, v68, v72
	v_fmac_f32_e32 v99, v68, v73
	v_fmac_f32_e32 v101, v68, v74
	v_fmac_f32_e32 v103, v68, v75
	ds_read_b128 v[72:75], v110 offset:18480
	v_fmac_f32_e32 v95, v68, v123
	s_waitcnt lgkmcnt(1)
	v_fmac_f32_e32 v89, v69, v76
	v_fmac_f32_e32 v91, v69, v77
	v_fmac_f32_e32 v93, v69, v78
	v_fmac_f32_e32 v95, v69, v79
	s_waitcnt lgkmcnt(0)
	v_fmac_f32_e32 v97, v69, v72
	ds_read_b128 v[76:79], v110 offset:18496
	v_fmac_f32_e32 v99, v69, v73
	v_fmac_f32_e32 v101, v69, v74
	v_fmac_f32_e32 v103, v69, v75
	ds_read_b128 v[72:75], v110 offset:18512
	s_waitcnt lgkmcnt(1)
	v_fmac_f32_e32 v89, v70, v76
	v_fmac_f32_e32 v91, v70, v77
	v_fmac_f32_e32 v93, v70, v78
	v_fmac_f32_e32 v95, v70, v79
	s_waitcnt lgkmcnt(0)
	v_fmac_f32_e32 v97, v70, v72
	ds_read_b128 v[76:79], v110 offset:18528
	v_fmac_f32_e32 v99, v70, v73
	v_fmac_f32_e32 v101, v70, v74
	v_fmac_f32_e32 v103, v70, v75
	ds_read_b128 v[72:75], v110 offset:18544
	s_waitcnt lgkmcnt(1)
	v_fmac_f32_e32 v89, v71, v76
	v_fmac_f32_e32 v91, v71, v77
	v_fmac_f32_e32 v93, v71, v78
	v_fmac_f32_e32 v95, v71, v79
	s_waitcnt lgkmcnt(0)
	v_fmac_f32_e32 v97, v71, v72
	ds_read_b128 v[76:79], v110 offset:27648
	v_fmac_f32_e32 v99, v71, v73
	v_fmac_f32_e32 v101, v71, v74
	v_fmac_f32_e32 v103, v71, v75
	ds_read_b128 v[68:71], v110 offset:27664
	ds_read_b128 v[72:75], v110 offset:27680
	s_waitcnt lgkmcnt(2)
	v_fmac_f32_e32 v89, v64, v76
	v_fmac_f32_e32 v91, v64, v77
	v_fmac_f32_e32 v93, v64, v78
	s_waitcnt lgkmcnt(1)
	v_fmac_f32_e32 v97, v64, v68
	v_fmac_f32_e32 v99, v64, v69
	v_fmac_f32_e32 v101, v64, v70
	v_fmac_f32_e32 v103, v64, v71
	ds_read_b128 v[68:71], v110 offset:27696
	v_fmac_f32_e32 v95, v64, v79
	s_waitcnt lgkmcnt(1)
	v_fmac_f32_e32 v89, v65, v72
	v_fmac_f32_e32 v91, v65, v73
	v_fmac_f32_e32 v93, v65, v74
	v_fmac_f32_e32 v95, v65, v75
	ds_read_b128 v[72:75], v110 offset:27712
	ds_read_b128 v[76:79], v110 offset:27744
	s_waitcnt lgkmcnt(2)
	v_fmac_f32_e32 v97, v65, v68
	v_fmac_f32_e32 v99, v65, v69
	v_fmac_f32_e32 v101, v65, v70
	v_fmac_f32_e32 v103, v65, v71
	ds_read_b128 v[68:71], v110 offset:27728
	s_waitcnt lgkmcnt(2)
	v_fmac_f32_e32 v91, v66, v73
	v_fmac_f32_e32 v89, v66, v72
	v_fmac_f32_e32 v93, v66, v74
	v_fmac_f32_e32 v95, v66, v75
	ds_read_b128 v[72:75], v110 offset:27760
	s_waitcnt lgkmcnt(2)
	v_fmac_f32_e32 v91, v67, v77
	s_waitcnt lgkmcnt(1)
	v_fmac_f32_e32 v97, v66, v68
	v_fmac_f32_e32 v99, v66, v69
	v_fmac_f32_e32 v101, v66, v70
	v_fmac_f32_e32 v103, v66, v71
	ds_bpermute_b32 v66, v111, v91
	v_fmac_f32_e32 v93, v67, v78
	v_fmac_f32_e32 v89, v67, v76
	v_fmac_f32_e32 v95, v67, v79
	s_waitcnt lgkmcnt(1)
	v_fmac_f32_e32 v97, v67, v72
	s_waitcnt lgkmcnt(0)
	v_add_f32_e32 v66, v91, v66
	ds_bpermute_b32 v68, v112, v66
	v_fmac_f32_e32 v99, v67, v73
	v_fmac_f32_e32 v101, v67, v74
	v_fmac_f32_e32 v103, v67, v75
	ds_bpermute_b32 v67, v111, v93
	s_waitcnt lgkmcnt(1)
	v_add_f32_e32 v66, v66, v68
	ds_bpermute_b32 v68, v113, v66
	ds_bpermute_b32 v70, v111, v97
	ds_bpermute_b32 v64, v111, v89
	s_waitcnt lgkmcnt(3)
	v_add_f32_e32 v67, v93, v67
	ds_bpermute_b32 v69, v112, v67
	s_waitcnt lgkmcnt(3)
	v_add_f32_e32 v66, v66, v68
	ds_bpermute_b32 v68, v114, v66
	ds_bpermute_b32 v76, v111, v103
	s_waitcnt lgkmcnt(3)
	v_add_f32_e32 v64, v89, v64
	s_waitcnt lgkmcnt(2)
	v_add_f32_e32 v67, v67, v69
	ds_bpermute_b32 v69, v113, v67
	s_waitcnt lgkmcnt(2)
	v_add_f32_e32 v66, v66, v68
	ds_bpermute_b32 v68, v111, v95
	s_waitcnt lgkmcnt(2)
	v_add_f32_e32 v76, v103, v76
	ds_bpermute_b32 v65, v112, v64
	s_waitcnt lgkmcnt(2)
	v_add_f32_e32 v67, v67, v69
	v_add_f32_e32 v69, v97, v70
	s_waitcnt lgkmcnt(1)
	v_add_f32_e32 v68, v95, v68
	ds_bpermute_b32 v72, v112, v68
	ds_bpermute_b32 v70, v112, v69
	ds_bpermute_b32 v73, v114, v67
	ds_bpermute_b32 v79, v112, v76
	s_waitcnt lgkmcnt(4)
	v_add_f32_e32 v64, v64, v65
	s_waitcnt lgkmcnt(3)
	v_add_f32_e32 v68, v68, v72
	s_waitcnt lgkmcnt(2)
	v_add_f32_e32 v69, v69, v70
	ds_bpermute_b32 v72, v113, v68
	ds_bpermute_b32 v70, v113, v69
	s_waitcnt lgkmcnt(3)
	v_add_f32_e32 v67, v67, v73
	ds_bpermute_b32 v73, v115, v67
	s_waitcnt lgkmcnt(3)
	v_add_f32_e32 v76, v76, v79
	s_waitcnt lgkmcnt(2)
	v_add_f32_e32 v68, v68, v72
	s_waitcnt lgkmcnt(1)
	v_add_f32_e32 v70, v69, v70
	ds_bpermute_b32 v72, v114, v68
	ds_bpermute_b32 v74, v114, v70
	s_waitcnt lgkmcnt(2)
	v_add_f32_e32 v69, v67, v73
	ds_bpermute_b32 v65, v113, v64
	ds_bpermute_b32 v79, v113, v76
	s_waitcnt lgkmcnt(3)
	v_add_f32_e32 v68, v68, v72
	s_waitcnt lgkmcnt(2)
	v_add_f32_e32 v73, v70, v74
	ds_bpermute_b32 v75, v115, v68
	ds_bpermute_b32 v74, v115, v73
	s_waitcnt lgkmcnt(3)
	v_add_f32_e32 v64, v64, v65
	s_waitcnt lgkmcnt(2)
	v_add_f32_e32 v76, v76, v79
	ds_bpermute_b32 v65, v114, v64
	s_waitcnt lgkmcnt(2)
	v_add_f32_e32 v67, v68, v75
	ds_bpermute_b32 v75, v111, v99
	s_waitcnt lgkmcnt(2)
	v_add_f32_e32 v68, v73, v74
	ds_bpermute_b32 v74, v111, v101
	ds_bpermute_b32 v79, v114, v76
	s_waitcnt lgkmcnt(3)
	v_add_f32_e32 v64, v64, v65
	s_waitcnt lgkmcnt(2)
	v_add_f32_e32 v75, v99, v75
	ds_bpermute_b32 v77, v112, v75
	s_waitcnt lgkmcnt(2)
	v_add_f32_e32 v74, v101, v74
	ds_bpermute_b32 v78, v112, v74
	s_waitcnt lgkmcnt(2)
	v_add_f32_e32 v91, v76, v79
	ds_bpermute_b32 v65, v115, v64
	s_waitcnt lgkmcnt(2)
	v_add_f32_e32 v75, v75, v77
	ds_bpermute_b32 v77, v113, v75
	s_waitcnt lgkmcnt(2)
	v_add_f32_e32 v74, v74, v78
	ds_bpermute_b32 v78, v113, v74
	ds_bpermute_b32 v71, v115, v66
	ds_bpermute_b32 v93, v115, v91
	s_waitcnt lgkmcnt(3)
	v_add_f32_e32 v75, v75, v77
	ds_bpermute_b32 v77, v114, v75
	s_waitcnt lgkmcnt(3)
	v_add_f32_e32 v74, v74, v78
	ds_bpermute_b32 v78, v114, v74
	v_add_f32_e32 v64, v64, v65
	s_waitcnt lgkmcnt(3)
	v_add_f32_e32 v66, v66, v71
	s_waitcnt lgkmcnt(1)
	v_add_f32_e32 v75, v75, v77
	ds_bpermute_b32 v77, v115, v75
	s_waitcnt lgkmcnt(1)
	v_add_f32_e32 v74, v74, v78
	ds_bpermute_b32 v89, v115, v74
	ds_bpermute_b32 v65, v116, v64
	ds_bpermute_b32 v71, v116, v66
	s_waitcnt lgkmcnt(3)
	v_add_f32_e32 v78, v75, v77
	ds_bpermute_b32 v72, v116, v69
	s_waitcnt lgkmcnt(3)
	v_add_f32_e32 v76, v74, v89
	v_add_f32_e32 v74, v91, v93
	ds_bpermute_b32 v70, v116, v67
	ds_bpermute_b32 v73, v116, v68
	ds_bpermute_b32 v79, v116, v78
	ds_bpermute_b32 v77, v116, v76
	ds_bpermute_b32 v75, v116, v74
	s_and_saveexec_b64 s[20:21], s[2:3]
	s_cbranch_execz .LBB0_190
	v_lshl_add_u64 v[120:121], v[104:105], 2, s[12:13]
	global_store_dword v[120:121], v85, off
	global_load_dword v89, v83, s[58:59]
	v_fmamk_f32 v85, v85, 0x3a800000, v117
	v_mul_f32_e32 v91, 0x4b800000, v85
	v_cmp_gt_f32_e32 vcc, s76, v85
	s_waitcnt lgkmcnt(6)
	v_add_f32_e32 v66, v66, v71
	s_waitcnt lgkmcnt(5)
	v_add_f32_e32 v69, v69, v72
	v_cndmask_b32_e32 v85, v85, v91, vcc
	v_rsq_f32_e32 v85, v85
	v_add_f32_e32 v91, v64, v65
	v_mad_i64_i32 v[64:65], s[14:15], v104, 28, v[120:121]
	v_mul_f32_e32 v93, 0x45800000, v85
	v_cndmask_b32_e32 v85, v85, v93, vcc
	v_add_co_u32_e32 v64, vcc, s77, v64
	s_waitcnt lgkmcnt(4)
	v_add_f32_e32 v67, v67, v70
	v_addc_co_u32_e32 v65, vcc, 0, v65, vcc
	s_waitcnt vmcnt(0)
	v_fmac_f32_e32 v89, v85, v91
	global_store_dword v[64:65], v89, off
	global_load_dword v89, v83, s[58:59] offset:4
	s_waitcnt vmcnt(0)
	v_fmac_f32_e32 v89, v85, v66
	global_store_dword v[64:65], v89, off offset:4
	global_load_dword v66, v83, s[58:59] offset:8
	s_waitcnt vmcnt(0)
	v_fmac_f32_e32 v66, v85, v69
	global_store_dword v[64:65], v66, off offset:8
	global_load_dword v66, v83, s[58:59] offset:12
	s_waitcnt vmcnt(0)
	v_fmac_f32_e32 v66, v85, v67
	global_store_dword v[64:65], v66, off offset:12
	global_load_dword v66, v83, s[58:59] offset:16
	s_waitcnt lgkmcnt(3)
	v_add_f32_e32 v67, v68, v73
	s_waitcnt vmcnt(0)
	v_fmac_f32_e32 v66, v85, v67
	global_store_dword v[64:65], v66, off offset:16
	global_load_dword v66, v83, s[58:59] offset:20
	s_waitcnt lgkmcnt(2)
	v_add_f32_e32 v67, v78, v79
	s_waitcnt vmcnt(0)
	v_fmac_f32_e32 v66, v85, v67
	global_store_dword v[64:65], v66, off offset:20
	global_load_dword v66, v83, s[58:59] offset:24
	s_waitcnt lgkmcnt(1)
	v_add_f32_e32 v67, v76, v77
	s_waitcnt vmcnt(0)
	v_fmac_f32_e32 v66, v85, v67
	global_store_dword v[64:65], v66, off offset:24
	global_load_dword v66, v83, s[58:59] offset:28
	s_waitcnt lgkmcnt(0)
	v_add_f32_e32 v67, v74, v75
	s_waitcnt vmcnt(0)
	v_fmac_f32_e32 v66, v85, v67
	global_store_dword v[64:65], v66, off offset:28

.LBB0_195:
	s_or_b64 exec, exec, s[18:19]
	s_waitcnt vmcnt(19)
	v_mul_f32_e32 v66, v61, v61
	v_mul_f32_e32 v67, v63, v63
	v_fmac_f32_e32 v66, v60, v60
	v_fmac_f32_e32 v67, v62, v62
	v_ashrrev_i32_e32 v101, 31, v100
	v_add_f32_e32 v68, v66, v67
	v_and_b32_sdwa v67, v60, v118 dst_sel:DWORD dst_unused:UNUSED_PAD src0_sel:WORD_1 src1_sel:DWORD
	s_waitcnt lgkmcnt(7)
	v_cndmask_b32_e64 v65, v101, 0, s[10:11]
	v_cndmask_b32_e64 v64, v100, v106, s[10:11]
	v_add3_u32 v69, v60, v67, s75
	v_and_b32_sdwa v67, v63, v118 dst_sel:DWORD dst_unused:UNUSED_PAD src0_sel:WORD_1 src1_sel:DWORD
	s_waitcnt lgkmcnt(4)
	v_and_b32_sdwa v70, v61, v118 dst_sel:DWORD dst_unused:UNUSED_PAD src0_sel:WORD_1 src1_sel:DWORD
	v_lshlrev_b64 v[64:65], 11, v[64:65]
	v_and_b32_sdwa v66, v62, v118 dst_sel:DWORD dst_unused:UNUSED_PAD src0_sel:WORD_1 src1_sel:DWORD
	v_add3_u32 v67, v63, v67, s75
	v_add3_u32 v70, v61, v70, s75
	v_lshl_add_u64 v[64:65], v[108:109], 0, v[64:65]
	v_add3_u32 v66, v62, v66, s75
	v_and_b32_e32 v67, 0xffff0000, v67
	v_and_b32_e32 v70, 0xffff0000, v70
	v_mov_b32_e32 v95, v83
	v_or_b32_sdwa v67, v67, v66 dst_sel:DWORD dst_unused:UNUSED_PAD src0_sel:DWORD src1_sel:WORD_1
	v_or_b32_sdwa v66, v70, v69 dst_sel:DWORD dst_unused:UNUSED_PAD src0_sel:DWORD src1_sel:WORD_1
	v_lshl_add_u64 v[64:65], v[64:65], 0, v[94:95]
	global_store_dwordx2 v[64:65], v[66:67], off
	s_waitcnt vmcnt(19)
	v_mul_f32_e32 v66, v57, v57
	v_mul_f32_e32 v67, v59, v59
	v_fmac_f32_e32 v66, v56, v56
	v_fmac_f32_e32 v67, v58, v58
	v_add_f32_e32 v66, v66, v67
	v_and_b32_sdwa v67, v56, v118 dst_sel:DWORD dst_unused:UNUSED_PAD src0_sel:WORD_1 src1_sel:DWORD
	v_add3_u32 v69, v56, v67, s75
	v_and_b32_sdwa v67, v59, v118 dst_sel:DWORD dst_unused:UNUSED_PAD src0_sel:WORD_1 src1_sel:DWORD
	v_and_b32_sdwa v70, v57, v118 dst_sel:DWORD dst_unused:UNUSED_PAD src0_sel:WORD_1 src1_sel:DWORD
	v_add_f32_e32 v68, v68, v66
	v_and_b32_sdwa v66, v58, v118 dst_sel:DWORD dst_unused:UNUSED_PAD src0_sel:WORD_1 src1_sel:DWORD
	v_add3_u32 v67, v59, v67, s75
	v_add3_u32 v70, v57, v70, s75
	v_add3_u32 v66, v58, v66, s75
	v_and_b32_e32 v67, 0xffff0000, v67
	v_and_b32_e32 v70, 0xffff0000, v70
	v_or_b32_sdwa v67, v67, v66 dst_sel:DWORD dst_unused:UNUSED_PAD src0_sel:DWORD src1_sel:WORD_1
	v_or_b32_sdwa v66, v70, v69 dst_sel:DWORD dst_unused:UNUSED_PAD src0_sel:DWORD src1_sel:WORD_1
	global_store_dwordx2 v[64:65], v[66:67], off offset:512
	s_waitcnt vmcnt(19)
	v_mul_f32_e32 v66, v53, v53
	v_mul_f32_e32 v67, v55, v55
	v_fmac_f32_e32 v66, v52, v52
	v_fmac_f32_e32 v67, v54, v54
	s_waitcnt vmcnt(18)
	v_mul_f32_e32 v69, v49, v49
	v_mul_f32_e32 v70, v51, v51
	v_add_f32_e32 v66, v66, v67
	v_fmac_f32_e32 v69, v48, v48
	v_fmac_f32_e32 v70, v50, v50
	v_add_f32_e32 v66, v68, v66
	v_add_f32_e32 v69, v69, v70
	v_add_f32_e32 v66, v66, v69
	ds_bpermute_b32 v69, v111, v66
	v_and_b32_sdwa v70, v55, v118 dst_sel:DWORD dst_unused:UNUSED_PAD src0_sel:WORD_1 src1_sel:DWORD
	v_and_b32_sdwa v71, v53, v118 dst_sel:DWORD dst_unused:UNUSED_PAD src0_sel:WORD_1 src1_sel:DWORD
	v_and_b32_sdwa v67, v54, v118 dst_sel:DWORD dst_unused:UNUSED_PAD src0_sel:WORD_1 src1_sel:DWORD
	v_and_b32_sdwa v68, v52, v118 dst_sel:DWORD dst_unused:UNUSED_PAD src0_sel:WORD_1 src1_sel:DWORD
	s_waitcnt lgkmcnt(0)
	v_add_f32_e32 v66, v66, v69
	ds_bpermute_b32 v69, v112, v66
	v_add3_u32 v70, v55, v70, s75
	v_add3_u32 v71, v53, v71, s75
	v_add3_u32 v68, v52, v68, s75
	v_add3_u32 v67, v54, v67, s75
	s_waitcnt lgkmcnt(0)
	v_add_f32_e32 v69, v66, v69
	ds_bpermute_b32 v72, v113, v69
	v_and_b32_e32 v70, 0xffff0000, v70
	v_and_b32_e32 v71, 0xffff0000, v71
	v_or_b32_sdwa v67, v70, v67 dst_sel:DWORD dst_unused:UNUSED_PAD src0_sel:DWORD src1_sel:WORD_1
	v_or_b32_sdwa v66, v71, v68 dst_sel:DWORD dst_unused:UNUSED_PAD src0_sel:DWORD src1_sel:WORD_1
	global_store_dwordx2 v[64:65], v[66:67], off offset:1024
	s_waitcnt lgkmcnt(0)
	v_add_f32_e32 v67, v69, v72
	ds_bpermute_b32 v68, v114, v67
	v_and_b32_sdwa v70, v51, v118 dst_sel:DWORD dst_unused:UNUSED_PAD src0_sel:WORD_1 src1_sel:DWORD
	v_and_b32_sdwa v71, v49, v118 dst_sel:DWORD dst_unused:UNUSED_PAD src0_sel:WORD_1 src1_sel:DWORD
	v_and_b32_sdwa v66, v50, v118 dst_sel:DWORD dst_unused:UNUSED_PAD src0_sel:WORD_1 src1_sel:DWORD
	v_and_b32_sdwa v69, v48, v118 dst_sel:DWORD dst_unused:UNUSED_PAD src0_sel:WORD_1 src1_sel:DWORD
	s_waitcnt lgkmcnt(0)
	v_add_f32_e32 v67, v67, v68
	ds_bpermute_b32 v68, v115, v67
	v_add3_u32 v70, v51, v70, s75
	v_add3_u32 v71, v49, v71, s75
	v_add3_u32 v69, v48, v69, s75
	v_add3_u32 v66, v50, v66, s75
	s_waitcnt lgkmcnt(0)
	v_add_f32_e32 v68, v67, v68
	ds_bpermute_b32 v72, v116, v68
	v_and_b32_e32 v70, 0xffff0000, v70
	v_and_b32_e32 v71, 0xffff0000, v71
	v_or_b32_sdwa v67, v70, v66 dst_sel:DWORD dst_unused:UNUSED_PAD src0_sel:DWORD src1_sel:WORD_1
	v_or_b32_sdwa v66, v71, v69 dst_sel:DWORD dst_unused:UNUSED_PAD src0_sel:DWORD src1_sel:WORD_1
	global_store_dwordx2 v[64:65], v[66:67], off offset:1536
	s_waitcnt lgkmcnt(0)
	v_add_f32_e32 v64, v68, v72
	s_and_saveexec_b64 s[10:11], s[8:9]
	s_xor_b64 s[8:9], exec, s[10:11]
	s_cbranch_execz .LBB0_199
	ds_read_b128 v[66:69], v110
	ds_read_b128 v[70:73], v110 offset:16
	ds_read_b128 v[74:77], v110 offset:32
	ds_read_b128 v[104:107], v110 offset:48
	s_waitcnt lgkmcnt(3)
	v_fma_f32 v65, v60, v66, 0
	v_fma_f32 v78, v60, v67, 0
	v_fma_f32 v79, v60, v68, 0
	v_fma_f32 v85, v60, v69, 0
	s_waitcnt lgkmcnt(2)
	v_fma_f32 v89, v60, v70, 0
	v_fma_f32 v91, v60, v71, 0
	v_fma_f32 v93, v60, v72, 0
	v_fma_f32 v95, v60, v73, 0
	ds_read_b128 v[66:69], v110 offset:64
	ds_read_b128 v[70:73], v110 offset:80
	s_waitcnt lgkmcnt(3)
	v_fmac_f32_e32 v65, v61, v74
	v_fmac_f32_e32 v78, v61, v75
	v_fmac_f32_e32 v79, v61, v76
	v_fmac_f32_e32 v85, v61, v77
	s_waitcnt lgkmcnt(2)
	v_fmac_f32_e32 v89, v61, v104
	v_fmac_f32_e32 v91, v61, v105
	v_fmac_f32_e32 v93, v61, v106
	v_fmac_f32_e32 v95, v61, v107
	s_waitcnt lgkmcnt(1)
	v_fmac_f32_e32 v65, v62, v66
	v_fmac_f32_e32 v78, v62, v67
	v_fmac_f32_e32 v79, v62, v68
	v_fmac_f32_e32 v85, v62, v69
	s_waitcnt lgkmcnt(0)
	v_fmac_f32_e32 v89, v62, v70
	ds_read_b128 v[66:69], v110 offset:96
	v_fmac_f32_e32 v91, v62, v71
	v_fmac_f32_e32 v93, v62, v72
	v_fmac_f32_e32 v95, v62, v73
	ds_read_b128 v[70:73], v110 offset:112
	s_waitcnt lgkmcnt(1)
	v_fmac_f32_e32 v65, v63, v66
	v_fmac_f32_e32 v78, v63, v67
	v_fmac_f32_e32 v79, v63, v68
	v_fmac_f32_e32 v85, v63, v69
	s_waitcnt lgkmcnt(0)
	v_fmac_f32_e32 v89, v63, v70
	ds_read_b128 v[66:69], v110 offset:9216
	v_fmac_f32_e32 v91, v63, v71
	v_fmac_f32_e32 v93, v63, v72
	v_fmac_f32_e32 v95, v63, v73
	ds_read_b128 v[60:63], v110 offset:9232
	s_waitcnt lgkmcnt(1)
	v_fmac_f32_e32 v65, v56, v66
	v_fmac_f32_e32 v78, v56, v67
	v_fmac_f32_e32 v79, v56, v68
	v_fmac_f32_e32 v85, v56, v69
	s_waitcnt lgkmcnt(0)
	v_fmac_f32_e32 v89, v56, v60
	ds_read_b128 v[66:69], v110 offset:9248
	v_fmac_f32_e32 v91, v56, v61
	v_fmac_f32_e32 v93, v56, v62
	v_fmac_f32_e32 v95, v56, v63
	ds_read_b128 v[60:63], v110 offset:9264
	s_waitcnt lgkmcnt(1)
	v_fmac_f32_e32 v65, v57, v66
	v_fmac_f32_e32 v78, v57, v67
	v_fmac_f32_e32 v79, v57, v68
	v_fmac_f32_e32 v85, v57, v69
	s_waitcnt lgkmcnt(0)
	v_fmac_f32_e32 v89, v57, v60
	ds_read_b128 v[66:69], v110 offset:9280
	v_fmac_f32_e32 v91, v57, v61
	v_fmac_f32_e32 v93, v57, v62
	v_fmac_f32_e32 v95, v57, v63
	ds_read_b128 v[60:63], v110 offset:9296
	s_waitcnt lgkmcnt(1)
	v_fmac_f32_e32 v65, v58, v66
	v_fmac_f32_e32 v78, v58, v67
	v_fmac_f32_e32 v79, v58, v68
	v_fmac_f32_e32 v85, v58, v69
	s_waitcnt lgkmcnt(0)
	v_fmac_f32_e32 v89, v58, v60
	ds_read_b128 v[66:69], v110 offset:9312
	v_fmac_f32_e32 v91, v58, v61
	v_fmac_f32_e32 v93, v58, v62
	v_fmac_f32_e32 v95, v58, v63
	ds_read_b128 v[60:63], v110 offset:9328
	s_waitcnt lgkmcnt(1)
	v_fmac_f32_e32 v65, v59, v66
	v_fmac_f32_e32 v78, v59, v67
	v_fmac_f32_e32 v79, v59, v68
	v_fmac_f32_e32 v85, v59, v69
	s_waitcnt lgkmcnt(0)
	v_fmac_f32_e32 v89, v59, v60
	ds_read_b128 v[66:69], v110 offset:18432
	v_fmac_f32_e32 v91, v59, v61
	v_fmac_f32_e32 v93, v59, v62
	v_fmac_f32_e32 v95, v59, v63
	ds_read_b128 v[56:59], v110 offset:18448
	ds_read_b128 v[60:63], v110 offset:18464
	s_waitcnt lgkmcnt(2)
	v_fmac_f32_e32 v65, v52, v66
	v_fmac_f32_e32 v78, v52, v67
	v_fmac_f32_e32 v79, v52, v68
	s_waitcnt lgkmcnt(1)
	v_fmac_f32_e32 v89, v52, v56
	v_fmac_f32_e32 v91, v52, v57
	v_fmac_f32_e32 v93, v52, v58
	v_fmac_f32_e32 v95, v52, v59
	ds_read_b128 v[56:59], v110 offset:18480
	v_fmac_f32_e32 v85, v52, v69
	s_waitcnt lgkmcnt(1)
	v_fmac_f32_e32 v65, v53, v60
	v_fmac_f32_e32 v78, v53, v61
	v_fmac_f32_e32 v79, v53, v62
	v_fmac_f32_e32 v85, v53, v63
	s_waitcnt lgkmcnt(0)
	v_fmac_f32_e32 v89, v53, v56
	ds_read_b128 v[60:63], v110 offset:18496
	v_fmac_f32_e32 v91, v53, v57
	v_fmac_f32_e32 v93, v53, v58
	v_fmac_f32_e32 v95, v53, v59
	ds_read_b128 v[56:59], v110 offset:18512
	s_waitcnt lgkmcnt(1)
	v_fmac_f32_e32 v65, v54, v60
	v_fmac_f32_e32 v78, v54, v61
	v_fmac_f32_e32 v79, v54, v62
	v_fmac_f32_e32 v85, v54, v63
	s_waitcnt lgkmcnt(0)
	v_fmac_f32_e32 v89, v54, v56
	ds_read_b128 v[60:63], v110 offset:18528
	v_fmac_f32_e32 v91, v54, v57
	v_fmac_f32_e32 v93, v54, v58
	v_fmac_f32_e32 v95, v54, v59
	ds_read_b128 v[56:59], v110 offset:18544
	s_waitcnt lgkmcnt(1)
	v_fmac_f32_e32 v65, v55, v60
	v_fmac_f32_e32 v78, v55, v61
	v_fmac_f32_e32 v79, v55, v62
	v_fmac_f32_e32 v85, v55, v63
	s_waitcnt lgkmcnt(0)
	v_fmac_f32_e32 v89, v55, v56
	ds_read_b128 v[60:63], v110 offset:27648
	v_fmac_f32_e32 v91, v55, v57
	v_fmac_f32_e32 v93, v55, v58
	v_fmac_f32_e32 v95, v55, v59
	ds_read_b128 v[52:55], v110 offset:27664
	ds_read_b128 v[56:59], v110 offset:27680
	s_waitcnt lgkmcnt(2)
	v_fmac_f32_e32 v65, v48, v60
	v_fmac_f32_e32 v78, v48, v61
	v_fmac_f32_e32 v79, v48, v62
	s_waitcnt lgkmcnt(1)
	v_fmac_f32_e32 v89, v48, v52
	v_fmac_f32_e32 v91, v48, v53
	v_fmac_f32_e32 v93, v48, v54
	v_fmac_f32_e32 v95, v48, v55
	ds_read_b128 v[52:55], v110 offset:27696
	v_fmac_f32_e32 v85, v48, v63
	s_waitcnt lgkmcnt(1)
	v_fmac_f32_e32 v65, v49, v56
	v_fmac_f32_e32 v78, v49, v57
	v_fmac_f32_e32 v79, v49, v58
	v_fmac_f32_e32 v85, v49, v59
	ds_read_b128 v[56:59], v110 offset:27712
	ds_read_b128 v[60:63], v110 offset:27744
	s_waitcnt lgkmcnt(2)
	v_fmac_f32_e32 v89, v49, v52
	v_fmac_f32_e32 v91, v49, v53
	v_fmac_f32_e32 v93, v49, v54
	v_fmac_f32_e32 v95, v49, v55
	ds_read_b128 v[52:55], v110 offset:27728
	s_waitcnt lgkmcnt(2)
	v_fmac_f32_e32 v78, v50, v57
	v_fmac_f32_e32 v65, v50, v56
	v_fmac_f32_e32 v79, v50, v58
	v_fmac_f32_e32 v85, v50, v59
	ds_read_b128 v[56:59], v110 offset:27760
	s_waitcnt lgkmcnt(2)
	v_fmac_f32_e32 v78, v51, v61
	s_waitcnt lgkmcnt(1)
	v_fmac_f32_e32 v89, v50, v52
	v_fmac_f32_e32 v91, v50, v53
	v_fmac_f32_e32 v93, v50, v54
	v_fmac_f32_e32 v95, v50, v55
	ds_bpermute_b32 v50, v111, v78
	v_fmac_f32_e32 v79, v51, v62
	v_fmac_f32_e32 v65, v51, v60
	v_fmac_f32_e32 v85, v51, v63
	s_waitcnt lgkmcnt(1)
	v_fmac_f32_e32 v89, v51, v56
	s_waitcnt lgkmcnt(0)
	v_add_f32_e32 v50, v78, v50
	ds_bpermute_b32 v52, v112, v50
	v_fmac_f32_e32 v91, v51, v57
	v_fmac_f32_e32 v93, v51, v58
	v_fmac_f32_e32 v95, v51, v59
	ds_bpermute_b32 v51, v111, v79
	s_waitcnt lgkmcnt(1)
	v_add_f32_e32 v50, v50, v52
	ds_bpermute_b32 v52, v113, v50
	ds_bpermute_b32 v54, v111, v89
	ds_bpermute_b32 v48, v111, v65
	s_waitcnt lgkmcnt(3)
	v_add_f32_e32 v51, v79, v51
	ds_bpermute_b32 v53, v112, v51
	s_waitcnt lgkmcnt(3)
	v_add_f32_e32 v50, v50, v52
	ds_bpermute_b32 v52, v114, v50
	ds_bpermute_b32 v60, v111, v95
	s_waitcnt lgkmcnt(3)
	v_add_f32_e32 v48, v65, v48
	s_waitcnt lgkmcnt(2)
	v_add_f32_e32 v51, v51, v53
	ds_bpermute_b32 v53, v113, v51
	s_waitcnt lgkmcnt(2)
	v_add_f32_e32 v50, v50, v52
	ds_bpermute_b32 v52, v111, v85
	s_waitcnt lgkmcnt(2)
	v_add_f32_e32 v60, v95, v60
	ds_bpermute_b32 v49, v112, v48
	s_waitcnt lgkmcnt(2)
	v_add_f32_e32 v51, v51, v53
	v_add_f32_e32 v53, v89, v54
	s_waitcnt lgkmcnt(1)
	v_add_f32_e32 v52, v85, v52
	ds_bpermute_b32 v56, v112, v52
	ds_bpermute_b32 v54, v112, v53
	ds_bpermute_b32 v57, v114, v51
	ds_bpermute_b32 v63, v112, v60
	s_waitcnt lgkmcnt(4)
	v_add_f32_e32 v48, v48, v49
	s_waitcnt lgkmcnt(3)
	v_add_f32_e32 v52, v52, v56
	s_waitcnt lgkmcnt(2)
	v_add_f32_e32 v53, v53, v54
	ds_bpermute_b32 v56, v113, v52
	ds_bpermute_b32 v54, v113, v53
	s_waitcnt lgkmcnt(3)
	v_add_f32_e32 v51, v51, v57
	ds_bpermute_b32 v57, v115, v51
	s_waitcnt lgkmcnt(3)
	v_add_f32_e32 v60, v60, v63
	s_waitcnt lgkmcnt(2)
	v_add_f32_e32 v52, v52, v56
	s_waitcnt lgkmcnt(1)
	v_add_f32_e32 v54, v53, v54
	ds_bpermute_b32 v56, v114, v52
	ds_bpermute_b32 v58, v114, v54
	s_waitcnt lgkmcnt(2)
	v_add_f32_e32 v53, v51, v57
	ds_bpermute_b32 v49, v113, v48
	ds_bpermute_b32 v63, v113, v60
	s_waitcnt lgkmcnt(3)
	v_add_f32_e32 v52, v52, v56
	s_waitcnt lgkmcnt(2)
	v_add_f32_e32 v57, v54, v58
	ds_bpermute_b32 v59, v115, v52
	ds_bpermute_b32 v58, v115, v57
	s_waitcnt lgkmcnt(3)
	v_add_f32_e32 v48, v48, v49
	s_waitcnt lgkmcnt(2)
	v_add_f32_e32 v60, v60, v63
	ds_bpermute_b32 v49, v114, v48
	s_waitcnt lgkmcnt(2)
	v_add_f32_e32 v51, v52, v59
	ds_bpermute_b32 v59, v111, v91
	s_waitcnt lgkmcnt(2)
	v_add_f32_e32 v52, v57, v58
	ds_bpermute_b32 v58, v111, v93
	ds_bpermute_b32 v63, v114, v60
	s_waitcnt lgkmcnt(3)
	v_add_f32_e32 v48, v48, v49
	s_waitcnt lgkmcnt(2)
	v_add_f32_e32 v59, v91, v59
	ds_bpermute_b32 v61, v112, v59
	s_waitcnt lgkmcnt(2)
	v_add_f32_e32 v58, v93, v58
	ds_bpermute_b32 v62, v112, v58
	s_waitcnt lgkmcnt(2)
	v_add_f32_e32 v66, v60, v63
	ds_bpermute_b32 v49, v115, v48
	s_waitcnt lgkmcnt(2)
	v_add_f32_e32 v59, v59, v61
	ds_bpermute_b32 v61, v113, v59
	s_waitcnt lgkmcnt(2)
	v_add_f32_e32 v58, v58, v62
	ds_bpermute_b32 v62, v113, v58
	ds_bpermute_b32 v55, v115, v50
	ds_bpermute_b32 v67, v115, v66
	s_waitcnt lgkmcnt(3)
	v_add_f32_e32 v59, v59, v61
	ds_bpermute_b32 v61, v114, v59
	s_waitcnt lgkmcnt(3)
	v_add_f32_e32 v58, v58, v62
	ds_bpermute_b32 v62, v114, v58
	v_add_f32_e32 v48, v48, v49
	s_waitcnt lgkmcnt(3)
	v_add_f32_e32 v50, v50, v55
	s_waitcnt lgkmcnt(1)
	v_add_f32_e32 v59, v59, v61
	ds_bpermute_b32 v61, v115, v59
	s_waitcnt lgkmcnt(1)
	v_add_f32_e32 v58, v58, v62
	ds_bpermute_b32 v65, v115, v58
	ds_bpermute_b32 v49, v116, v48
	ds_bpermute_b32 v55, v116, v50
	s_waitcnt lgkmcnt(3)
	v_add_f32_e32 v62, v59, v61
	ds_bpermute_b32 v56, v116, v53
	s_waitcnt lgkmcnt(3)
	v_add_f32_e32 v60, v58, v65
	v_add_f32_e32 v58, v66, v67
	ds_bpermute_b32 v54, v116, v51
	ds_bpermute_b32 v57, v116, v52
	ds_bpermute_b32 v63, v116, v62
	ds_bpermute_b32 v61, v116, v60
	ds_bpermute_b32 v59, v116, v58
	s_and_saveexec_b64 s[10:11], s[2:3]
	s_cbranch_execz .LBB0_198
	v_lshl_add_u64 v[66:67], v[100:101], 2, s[12:13]
	global_store_dword v[66:67], v64, off
	global_load_dword v65, v83, s[58:59]
	v_fmamk_f32 v64, v64, 0x3a800000, v117
	v_mul_f32_e32 v68, 0x4b800000, v64
	v_cmp_gt_f32_e32 vcc, s76, v64
	s_waitcnt lgkmcnt(6)
	v_add_f32_e32 v50, v50, v55
	s_waitcnt lgkmcnt(5)
	v_add_f32_e32 v53, v53, v56
	v_cndmask_b32_e32 v64, v64, v68, vcc
	v_rsq_f32_e32 v64, v64
	v_add_f32_e32 v68, v48, v49
	v_mad_i64_i32 v[48:49], s[14:15], v100, 28, v[66:67]
	v_mul_f32_e32 v66, 0x45800000, v64
	v_cndmask_b32_e32 v64, v64, v66, vcc
	v_add_co_u32_e32 v48, vcc, s77, v48
	s_waitcnt lgkmcnt(4)
	v_add_f32_e32 v51, v51, v54
	v_addc_co_u32_e32 v49, vcc, 0, v49, vcc
	s_waitcnt vmcnt(0)
	v_fmac_f32_e32 v65, v64, v68
	global_store_dword v[48:49], v65, off
	global_load_dword v65, v83, s[58:59] offset:4
	s_waitcnt vmcnt(0)
	v_fmac_f32_e32 v65, v64, v50
	global_store_dword v[48:49], v65, off offset:4
	global_load_dword v50, v83, s[58:59] offset:8
	s_waitcnt vmcnt(0)
	v_fmac_f32_e32 v50, v64, v53
	global_store_dword v[48:49], v50, off offset:8
	global_load_dword v50, v83, s[58:59] offset:12
	s_waitcnt vmcnt(0)
	v_fmac_f32_e32 v50, v64, v51
	global_store_dword v[48:49], v50, off offset:12
	global_load_dword v50, v83, s[58:59] offset:16
	s_waitcnt lgkmcnt(3)
	v_add_f32_e32 v51, v52, v57
	s_waitcnt vmcnt(0)
	v_fmac_f32_e32 v50, v64, v51
	global_store_dword v[48:49], v50, off offset:16
	global_load_dword v50, v83, s[58:59] offset:20
	s_waitcnt lgkmcnt(2)
	v_add_f32_e32 v51, v62, v63
	s_waitcnt vmcnt(0)
	v_fmac_f32_e32 v50, v64, v51
	global_store_dword v[48:49], v50, off offset:20
	global_load_dword v50, v83, s[58:59] offset:24
	s_waitcnt lgkmcnt(1)
	v_add_f32_e32 v51, v60, v61
	s_waitcnt vmcnt(0)
	v_fmac_f32_e32 v50, v64, v51
	global_store_dword v[48:49], v50, off offset:24
	global_load_dword v50, v83, s[58:59] offset:28
	s_waitcnt lgkmcnt(0)
	v_add_f32_e32 v51, v58, v59
	s_waitcnt vmcnt(0)
	v_fmac_f32_e32 v50, v64, v51
	global_store_dword v[48:49], v50, off offset:28

.LBB0_203:
	s_or_b64 exec, exec, s[8:9]
	v_mov_b32_e32 v48, s65
	s_waitcnt lgkmcnt(7)
	v_mov_b32_e32 v49, s57
	v_cndmask_b32_e64 v49, v48, v49, s[6:7]
	v_mov_b32_e32 v48, s64
	v_mov_b32_e32 v52, s56
	v_cndmask_b32_e64 v48, v48, v52, s[6:7]
	s_waitcnt vmcnt(19)
	v_mul_f32_e32 v52, v45, v45
	v_mul_f32_e32 v53, v47, v47
	v_fmac_f32_e32 v52, v44, v44
	v_fmac_f32_e32 v53, v46, v46
	v_ashrrev_i32_e32 v97, 31, v96
	s_waitcnt lgkmcnt(4)
	v_add_f32_e32 v54, v52, v53
	v_and_b32_sdwa v53, v44, v118 dst_sel:DWORD dst_unused:UNUSED_PAD src0_sel:WORD_1 src1_sel:DWORD
	v_cndmask_b32_e64 v51, v97, 0, s[6:7]
	v_cndmask_b32_e64 v50, v96, v102, s[6:7]
	v_add3_u32 v55, v44, v53, s75
	v_and_b32_sdwa v53, v47, v118 dst_sel:DWORD dst_unused:UNUSED_PAD src0_sel:WORD_1 src1_sel:DWORD
	v_and_b32_sdwa v56, v45, v118 dst_sel:DWORD dst_unused:UNUSED_PAD src0_sel:WORD_1 src1_sel:DWORD
	v_lshlrev_b64 v[50:51], 11, v[50:51]
	v_and_b32_sdwa v52, v46, v118 dst_sel:DWORD dst_unused:UNUSED_PAD src0_sel:WORD_1 src1_sel:DWORD
	v_add3_u32 v53, v47, v53, s75
	v_add3_u32 v56, v45, v56, s75
	v_lshl_add_u64 v[50:51], v[48:49], 0, v[50:51]
	v_add3_u32 v52, v46, v52, s75
	v_and_b32_e32 v53, 0xffff0000, v53
	v_and_b32_e32 v56, 0xffff0000, v56
	v_mov_b32_e32 v95, v83
	v_or_b32_sdwa v53, v53, v52 dst_sel:DWORD dst_unused:UNUSED_PAD src0_sel:DWORD src1_sel:WORD_1
	v_or_b32_sdwa v52, v56, v55 dst_sel:DWORD dst_unused:UNUSED_PAD src0_sel:DWORD src1_sel:WORD_1
	v_lshl_add_u64 v[50:51], v[50:51], 0, v[94:95]
	global_store_dwordx2 v[50:51], v[52:53], off
	s_waitcnt vmcnt(19)
	v_mul_f32_e32 v52, v41, v41
	v_mul_f32_e32 v53, v43, v43
	v_fmac_f32_e32 v52, v40, v40
	v_fmac_f32_e32 v53, v42, v42
	v_add_f32_e32 v52, v52, v53
	v_and_b32_sdwa v53, v40, v118 dst_sel:DWORD dst_unused:UNUSED_PAD src0_sel:WORD_1 src1_sel:DWORD
	v_add3_u32 v55, v40, v53, s75
	v_and_b32_sdwa v53, v43, v118 dst_sel:DWORD dst_unused:UNUSED_PAD src0_sel:WORD_1 src1_sel:DWORD
	v_and_b32_sdwa v56, v41, v118 dst_sel:DWORD dst_unused:UNUSED_PAD src0_sel:WORD_1 src1_sel:DWORD
	v_add_f32_e32 v54, v54, v52
	v_and_b32_sdwa v52, v42, v118 dst_sel:DWORD dst_unused:UNUSED_PAD src0_sel:WORD_1 src1_sel:DWORD
	v_add3_u32 v53, v43, v53, s75
	v_add3_u32 v56, v41, v56, s75
	v_add3_u32 v52, v42, v52, s75
	v_and_b32_e32 v53, 0xffff0000, v53
	v_and_b32_e32 v56, 0xffff0000, v56
	v_or_b32_sdwa v53, v53, v52 dst_sel:DWORD dst_unused:UNUSED_PAD src0_sel:DWORD src1_sel:WORD_1
	v_or_b32_sdwa v52, v56, v55 dst_sel:DWORD dst_unused:UNUSED_PAD src0_sel:DWORD src1_sel:WORD_1
	global_store_dwordx2 v[50:51], v[52:53], off offset:512
	s_waitcnt vmcnt(19)
	v_mul_f32_e32 v52, v37, v37
	v_mul_f32_e32 v53, v39, v39
	v_fmac_f32_e32 v52, v36, v36
	v_fmac_f32_e32 v53, v38, v38
	s_waitcnt vmcnt(18)
	v_mul_f32_e32 v55, v33, v33
	v_mul_f32_e32 v56, v35, v35
	v_add_f32_e32 v52, v52, v53
	v_fmac_f32_e32 v55, v32, v32
	v_fmac_f32_e32 v56, v34, v34
	v_add_f32_e32 v52, v54, v52
	v_add_f32_e32 v55, v55, v56
	v_add_f32_e32 v52, v52, v55
	ds_bpermute_b32 v55, v111, v52
	v_and_b32_sdwa v56, v39, v118 dst_sel:DWORD dst_unused:UNUSED_PAD src0_sel:WORD_1 src1_sel:DWORD
	s_waitcnt lgkmcnt(4)
	v_and_b32_sdwa v57, v37, v118 dst_sel:DWORD dst_unused:UNUSED_PAD src0_sel:WORD_1 src1_sel:DWORD
	v_and_b32_sdwa v53, v38, v118 dst_sel:DWORD dst_unused:UNUSED_PAD src0_sel:WORD_1 src1_sel:DWORD
	v_and_b32_sdwa v54, v36, v118 dst_sel:DWORD dst_unused:UNUSED_PAD src0_sel:WORD_1 src1_sel:DWORD
	s_waitcnt lgkmcnt(0)
	v_add_f32_e32 v52, v52, v55
	ds_bpermute_b32 v55, v112, v52
	v_add3_u32 v56, v39, v56, s75
	v_add3_u32 v57, v37, v57, s75
	v_add3_u32 v54, v36, v54, s75
	v_add3_u32 v53, v38, v53, s75
	s_waitcnt lgkmcnt(0)
	v_add_f32_e32 v55, v52, v55
	ds_bpermute_b32 v58, v113, v55
	v_and_b32_e32 v56, 0xffff0000, v56
	v_and_b32_e32 v57, 0xffff0000, v57
	v_or_b32_sdwa v53, v56, v53 dst_sel:DWORD dst_unused:UNUSED_PAD src0_sel:DWORD src1_sel:WORD_1
	v_or_b32_sdwa v52, v57, v54 dst_sel:DWORD dst_unused:UNUSED_PAD src0_sel:DWORD src1_sel:WORD_1
	global_store_dwordx2 v[50:51], v[52:53], off offset:1024
	s_waitcnt lgkmcnt(0)
	v_add_f32_e32 v53, v55, v58
	ds_bpermute_b32 v54, v114, v53
	v_and_b32_sdwa v56, v35, v118 dst_sel:DWORD dst_unused:UNUSED_PAD src0_sel:WORD_1 src1_sel:DWORD
	v_and_b32_sdwa v57, v33, v118 dst_sel:DWORD dst_unused:UNUSED_PAD src0_sel:WORD_1 src1_sel:DWORD
	v_and_b32_sdwa v52, v34, v118 dst_sel:DWORD dst_unused:UNUSED_PAD src0_sel:WORD_1 src1_sel:DWORD
	v_and_b32_sdwa v55, v32, v118 dst_sel:DWORD dst_unused:UNUSED_PAD src0_sel:WORD_1 src1_sel:DWORD
	s_waitcnt lgkmcnt(0)
	v_add_f32_e32 v53, v53, v54
	ds_bpermute_b32 v54, v115, v53
	v_add3_u32 v56, v35, v56, s75
	v_add3_u32 v57, v33, v57, s75
	v_add3_u32 v55, v32, v55, s75
	v_add3_u32 v52, v34, v52, s75
	s_waitcnt lgkmcnt(0)
	v_add_f32_e32 v54, v53, v54
	ds_bpermute_b32 v58, v116, v54
	v_and_b32_e32 v56, 0xffff0000, v56
	v_and_b32_e32 v57, 0xffff0000, v57
	v_or_b32_sdwa v53, v56, v52 dst_sel:DWORD dst_unused:UNUSED_PAD src0_sel:DWORD src1_sel:WORD_1
	v_or_b32_sdwa v52, v57, v55 dst_sel:DWORD dst_unused:UNUSED_PAD src0_sel:DWORD src1_sel:WORD_1
	global_store_dwordx2 v[50:51], v[52:53], off offset:1536
	s_waitcnt lgkmcnt(0)
	v_add_f32_e32 v50, v54, v58
	s_and_saveexec_b64 s[8:9], s[4:5]
	s_xor_b64 s[8:9], exec, s[8:9]
	s_cbranch_execz .LBB0_207
	ds_read_b128 v[52:55], v110
	ds_read_b128 v[56:59], v110 offset:16
	ds_read_b128 v[60:63], v110 offset:32
	ds_read_b128 v[64:67], v110 offset:48
	s_waitcnt lgkmcnt(3)
	v_fma_f32 v51, v44, v52, 0
	v_fma_f32 v68, v44, v53, 0
	v_fma_f32 v69, v44, v54, 0
	v_fma_f32 v70, v44, v55, 0
	s_waitcnt lgkmcnt(2)
	v_fma_f32 v71, v44, v56, 0
	v_fma_f32 v72, v44, v57, 0
	v_fma_f32 v73, v44, v58, 0
	v_fma_f32 v74, v44, v59, 0
	ds_read_b128 v[52:55], v110 offset:64
	ds_read_b128 v[56:59], v110 offset:80
	s_waitcnt lgkmcnt(3)
	v_fmac_f32_e32 v51, v45, v60
	v_fmac_f32_e32 v68, v45, v61
	v_fmac_f32_e32 v69, v45, v62
	v_fmac_f32_e32 v70, v45, v63
	s_waitcnt lgkmcnt(2)
	v_fmac_f32_e32 v71, v45, v64
	v_fmac_f32_e32 v72, v45, v65
	v_fmac_f32_e32 v73, v45, v66
	v_fmac_f32_e32 v74, v45, v67
	s_waitcnt lgkmcnt(1)
	v_fmac_f32_e32 v51, v46, v52
	v_fmac_f32_e32 v68, v46, v53
	v_fmac_f32_e32 v69, v46, v54
	v_fmac_f32_e32 v70, v46, v55
	s_waitcnt lgkmcnt(0)
	v_fmac_f32_e32 v71, v46, v56
	ds_read_b128 v[52:55], v110 offset:96
	v_fmac_f32_e32 v72, v46, v57
	v_fmac_f32_e32 v73, v46, v58
	v_fmac_f32_e32 v74, v46, v59
	ds_read_b128 v[56:59], v110 offset:112
	s_waitcnt lgkmcnt(1)
	v_fmac_f32_e32 v51, v47, v52
	v_fmac_f32_e32 v68, v47, v53
	v_fmac_f32_e32 v69, v47, v54
	v_fmac_f32_e32 v70, v47, v55
	s_waitcnt lgkmcnt(0)
	v_fmac_f32_e32 v71, v47, v56
	ds_read_b128 v[52:55], v110 offset:9216
	v_fmac_f32_e32 v72, v47, v57
	v_fmac_f32_e32 v73, v47, v58
	v_fmac_f32_e32 v74, v47, v59
	ds_read_b128 v[44:47], v110 offset:9232
	s_waitcnt lgkmcnt(1)
	v_fmac_f32_e32 v51, v40, v52
	v_fmac_f32_e32 v68, v40, v53
	v_fmac_f32_e32 v69, v40, v54
	v_fmac_f32_e32 v70, v40, v55
	s_waitcnt lgkmcnt(0)
	v_fmac_f32_e32 v71, v40, v44
	ds_read_b128 v[52:55], v110 offset:9248
	v_fmac_f32_e32 v72, v40, v45
	v_fmac_f32_e32 v73, v40, v46
	v_fmac_f32_e32 v74, v40, v47
	ds_read_b128 v[44:47], v110 offset:9264
	s_waitcnt lgkmcnt(1)
	v_fmac_f32_e32 v51, v41, v52
	v_fmac_f32_e32 v68, v41, v53
	v_fmac_f32_e32 v69, v41, v54
	v_fmac_f32_e32 v70, v41, v55
	s_waitcnt lgkmcnt(0)
	v_fmac_f32_e32 v71, v41, v44
	ds_read_b128 v[52:55], v110 offset:9280
	v_fmac_f32_e32 v72, v41, v45
	v_fmac_f32_e32 v73, v41, v46
	v_fmac_f32_e32 v74, v41, v47
	ds_read_b128 v[44:47], v110 offset:9296
	s_waitcnt lgkmcnt(1)
	v_fmac_f32_e32 v51, v42, v52
	v_fmac_f32_e32 v68, v42, v53
	v_fmac_f32_e32 v69, v42, v54
	v_fmac_f32_e32 v70, v42, v55
	s_waitcnt lgkmcnt(0)
	v_fmac_f32_e32 v71, v42, v44
	ds_read_b128 v[52:55], v110 offset:9312
	v_fmac_f32_e32 v72, v42, v45
	v_fmac_f32_e32 v73, v42, v46
	v_fmac_f32_e32 v74, v42, v47
	ds_read_b128 v[44:47], v110 offset:9328
	s_waitcnt lgkmcnt(1)
	v_fmac_f32_e32 v51, v43, v52
	v_fmac_f32_e32 v68, v43, v53
	v_fmac_f32_e32 v69, v43, v54
	v_fmac_f32_e32 v70, v43, v55
	s_waitcnt lgkmcnt(0)
	v_fmac_f32_e32 v71, v43, v44
	ds_read_b128 v[52:55], v110 offset:18432
	v_fmac_f32_e32 v72, v43, v45
	v_fmac_f32_e32 v73, v43, v46
	v_fmac_f32_e32 v74, v43, v47
	ds_read_b128 v[40:43], v110 offset:18448
	ds_read_b128 v[44:47], v110 offset:18464
	s_waitcnt lgkmcnt(2)
	v_fmac_f32_e32 v51, v36, v52
	v_fmac_f32_e32 v68, v36, v53
	v_fmac_f32_e32 v69, v36, v54
	s_waitcnt lgkmcnt(1)
	v_fmac_f32_e32 v71, v36, v40
	v_fmac_f32_e32 v72, v36, v41
	v_fmac_f32_e32 v73, v36, v42
	v_fmac_f32_e32 v74, v36, v43
	ds_read_b128 v[40:43], v110 offset:18480
	v_fmac_f32_e32 v70, v36, v55
	s_waitcnt lgkmcnt(1)
	v_fmac_f32_e32 v51, v37, v44
	v_fmac_f32_e32 v68, v37, v45
	v_fmac_f32_e32 v69, v37, v46
	v_fmac_f32_e32 v70, v37, v47
	s_waitcnt lgkmcnt(0)
	v_fmac_f32_e32 v71, v37, v40
	ds_read_b128 v[44:47], v110 offset:18496
	v_fmac_f32_e32 v72, v37, v41
	v_fmac_f32_e32 v73, v37, v42
	v_fmac_f32_e32 v74, v37, v43
	ds_read_b128 v[40:43], v110 offset:18512
	s_waitcnt lgkmcnt(1)
	v_fmac_f32_e32 v51, v38, v44
	v_fmac_f32_e32 v68, v38, v45
	v_fmac_f32_e32 v69, v38, v46
	v_fmac_f32_e32 v70, v38, v47
	s_waitcnt lgkmcnt(0)
	v_fmac_f32_e32 v71, v38, v40
	ds_read_b128 v[44:47], v110 offset:18528
	v_fmac_f32_e32 v72, v38, v41
	v_fmac_f32_e32 v73, v38, v42
	v_fmac_f32_e32 v74, v38, v43
	ds_read_b128 v[40:43], v110 offset:18544
	s_waitcnt lgkmcnt(1)
	v_fmac_f32_e32 v51, v39, v44
	v_fmac_f32_e32 v68, v39, v45
	v_fmac_f32_e32 v69, v39, v46
	v_fmac_f32_e32 v70, v39, v47
	s_waitcnt lgkmcnt(0)
	v_fmac_f32_e32 v71, v39, v40
	ds_read_b128 v[44:47], v110 offset:27648
	v_fmac_f32_e32 v72, v39, v41
	v_fmac_f32_e32 v73, v39, v42
	v_fmac_f32_e32 v74, v39, v43
	ds_read_b128 v[36:39], v110 offset:27664
	ds_read_b128 v[40:43], v110 offset:27680
	s_waitcnt lgkmcnt(2)
	v_fmac_f32_e32 v51, v32, v44
	v_fmac_f32_e32 v68, v32, v45
	v_fmac_f32_e32 v69, v32, v46
	s_waitcnt lgkmcnt(1)
	v_fmac_f32_e32 v71, v32, v36
	v_fmac_f32_e32 v72, v32, v37
	v_fmac_f32_e32 v73, v32, v38
	v_fmac_f32_e32 v74, v32, v39
	ds_read_b128 v[36:39], v110 offset:27696
	v_fmac_f32_e32 v70, v32, v47
	s_waitcnt lgkmcnt(1)
	v_fmac_f32_e32 v51, v33, v40
	v_fmac_f32_e32 v68, v33, v41
	v_fmac_f32_e32 v69, v33, v42
	v_fmac_f32_e32 v70, v33, v43
	ds_read_b128 v[40:43], v110 offset:27712
	ds_read_b128 v[44:47], v110 offset:27744
	s_waitcnt lgkmcnt(2)
	v_fmac_f32_e32 v71, v33, v36
	v_fmac_f32_e32 v72, v33, v37
	v_fmac_f32_e32 v73, v33, v38
	v_fmac_f32_e32 v74, v33, v39
	ds_read_b128 v[36:39], v110 offset:27728
	s_waitcnt lgkmcnt(2)
	v_fmac_f32_e32 v68, v34, v41
	v_fmac_f32_e32 v51, v34, v40
	v_fmac_f32_e32 v69, v34, v42
	v_fmac_f32_e32 v70, v34, v43
	ds_read_b128 v[40:43], v110 offset:27760
	s_waitcnt lgkmcnt(2)
	v_fmac_f32_e32 v68, v35, v45
	s_waitcnt lgkmcnt(1)
	v_fmac_f32_e32 v71, v34, v36
	v_fmac_f32_e32 v72, v34, v37
	v_fmac_f32_e32 v73, v34, v38
	v_fmac_f32_e32 v74, v34, v39
	ds_bpermute_b32 v34, v111, v68
	v_fmac_f32_e32 v69, v35, v46
	v_fmac_f32_e32 v51, v35, v44
	v_fmac_f32_e32 v70, v35, v47
	s_waitcnt lgkmcnt(1)
	v_fmac_f32_e32 v71, v35, v40
	s_waitcnt lgkmcnt(0)
	v_add_f32_e32 v34, v68, v34
	ds_bpermute_b32 v36, v112, v34
	v_fmac_f32_e32 v72, v35, v41
	v_fmac_f32_e32 v73, v35, v42
	v_fmac_f32_e32 v74, v35, v43
	ds_bpermute_b32 v35, v111, v69
	s_waitcnt lgkmcnt(1)
	v_add_f32_e32 v34, v34, v36
	ds_bpermute_b32 v36, v113, v34
	ds_bpermute_b32 v38, v111, v71
	ds_bpermute_b32 v32, v111, v51
	s_waitcnt lgkmcnt(3)
	v_add_f32_e32 v35, v69, v35
	ds_bpermute_b32 v37, v112, v35
	s_waitcnt lgkmcnt(3)
	v_add_f32_e32 v34, v34, v36
	ds_bpermute_b32 v36, v114, v34
	ds_bpermute_b32 v44, v111, v74
	s_waitcnt lgkmcnt(3)
	v_add_f32_e32 v32, v51, v32
	s_waitcnt lgkmcnt(2)
	v_add_f32_e32 v35, v35, v37
	ds_bpermute_b32 v37, v113, v35
	s_waitcnt lgkmcnt(2)
	v_add_f32_e32 v34, v34, v36
	ds_bpermute_b32 v36, v111, v70
	s_waitcnt lgkmcnt(2)
	v_add_f32_e32 v44, v74, v44
	ds_bpermute_b32 v33, v112, v32
	s_waitcnt lgkmcnt(2)
	v_add_f32_e32 v35, v35, v37
	v_add_f32_e32 v37, v71, v38
	s_waitcnt lgkmcnt(1)
	v_add_f32_e32 v36, v70, v36
	ds_bpermute_b32 v40, v112, v36
	ds_bpermute_b32 v38, v112, v37
	ds_bpermute_b32 v41, v114, v35
	ds_bpermute_b32 v47, v112, v44
	s_waitcnt lgkmcnt(4)
	v_add_f32_e32 v32, v32, v33
	s_waitcnt lgkmcnt(3)
	v_add_f32_e32 v36, v36, v40
	s_waitcnt lgkmcnt(2)
	v_add_f32_e32 v37, v37, v38
	ds_bpermute_b32 v40, v113, v36
	ds_bpermute_b32 v38, v113, v37
	s_waitcnt lgkmcnt(3)
	v_add_f32_e32 v35, v35, v41
	ds_bpermute_b32 v41, v115, v35
	s_waitcnt lgkmcnt(3)
	v_add_f32_e32 v44, v44, v47
	s_waitcnt lgkmcnt(2)
	v_add_f32_e32 v36, v36, v40
	s_waitcnt lgkmcnt(1)
	v_add_f32_e32 v38, v37, v38
	ds_bpermute_b32 v40, v114, v36
	ds_bpermute_b32 v42, v114, v38
	s_waitcnt lgkmcnt(2)
	v_add_f32_e32 v37, v35, v41
	ds_bpermute_b32 v33, v113, v32
	ds_bpermute_b32 v47, v113, v44
	s_waitcnt lgkmcnt(3)
	v_add_f32_e32 v36, v36, v40
	s_waitcnt lgkmcnt(2)
	v_add_f32_e32 v41, v38, v42
	ds_bpermute_b32 v43, v115, v36
	ds_bpermute_b32 v42, v115, v41
	s_waitcnt lgkmcnt(3)
	v_add_f32_e32 v32, v32, v33
	s_waitcnt lgkmcnt(2)
	v_add_f32_e32 v44, v44, v47
	ds_bpermute_b32 v33, v114, v32
	s_waitcnt lgkmcnt(2)
	v_add_f32_e32 v35, v36, v43
	ds_bpermute_b32 v43, v111, v72
	s_waitcnt lgkmcnt(2)
	v_add_f32_e32 v36, v41, v42
	ds_bpermute_b32 v42, v111, v73
	ds_bpermute_b32 v47, v114, v44
	s_waitcnt lgkmcnt(3)
	v_add_f32_e32 v32, v32, v33
	s_waitcnt lgkmcnt(2)
	v_add_f32_e32 v43, v72, v43
	ds_bpermute_b32 v45, v112, v43
	s_waitcnt lgkmcnt(2)
	v_add_f32_e32 v42, v73, v42
	ds_bpermute_b32 v46, v112, v42
	s_waitcnt lgkmcnt(2)
	v_add_f32_e32 v52, v44, v47
	ds_bpermute_b32 v33, v115, v32
	s_waitcnt lgkmcnt(2)
	v_add_f32_e32 v43, v43, v45
	ds_bpermute_b32 v45, v113, v43
	s_waitcnt lgkmcnt(2)
	v_add_f32_e32 v42, v42, v46
	ds_bpermute_b32 v46, v113, v42
	ds_bpermute_b32 v39, v115, v34
	ds_bpermute_b32 v53, v115, v52
	s_waitcnt lgkmcnt(3)
	v_add_f32_e32 v43, v43, v45
	ds_bpermute_b32 v45, v114, v43
	s_waitcnt lgkmcnt(3)
	v_add_f32_e32 v42, v42, v46
	ds_bpermute_b32 v46, v114, v42
	v_add_f32_e32 v32, v32, v33
	s_waitcnt lgkmcnt(3)
	v_add_f32_e32 v34, v34, v39
	s_waitcnt lgkmcnt(1)
	v_add_f32_e32 v43, v43, v45
	ds_bpermute_b32 v45, v115, v43
	s_waitcnt lgkmcnt(1)
	v_add_f32_e32 v42, v42, v46
	ds_bpermute_b32 v51, v115, v42
	ds_bpermute_b32 v33, v116, v32
	ds_bpermute_b32 v39, v116, v34
	s_waitcnt lgkmcnt(3)
	v_add_f32_e32 v46, v43, v45
	ds_bpermute_b32 v40, v116, v37
	s_waitcnt lgkmcnt(3)
	v_add_f32_e32 v44, v42, v51
	v_add_f32_e32 v42, v52, v53
	ds_bpermute_b32 v38, v116, v35
	ds_bpermute_b32 v41, v116, v36
	ds_bpermute_b32 v47, v116, v46
	ds_bpermute_b32 v45, v116, v44
	ds_bpermute_b32 v43, v116, v42
	s_and_saveexec_b64 s[10:11], s[2:3]
	s_cbranch_execz .LBB0_206
	v_lshl_add_u64 v[52:53], v[96:97], 2, s[12:13]
	global_store_dword v[52:53], v50, off
	global_load_dword v51, v83, s[58:59]
	v_fmamk_f32 v50, v50, 0x3a800000, v117
	v_mul_f32_e32 v54, 0x4b800000, v50
	v_cmp_gt_f32_e32 vcc, s76, v50
	s_waitcnt lgkmcnt(6)
	v_add_f32_e32 v34, v34, v39
	s_waitcnt lgkmcnt(5)
	v_add_f32_e32 v37, v37, v40
	v_cndmask_b32_e32 v50, v50, v54, vcc
	v_rsq_f32_e32 v50, v50
	v_add_f32_e32 v54, v32, v33
	v_mad_i64_i32 v[32:33], s[14:15], v96, 28, v[52:53]
	v_mul_f32_e32 v52, 0x45800000, v50
	v_cndmask_b32_e32 v50, v50, v52, vcc
	v_add_co_u32_e32 v32, vcc, s77, v32
	s_waitcnt lgkmcnt(4)
	v_add_f32_e32 v35, v35, v38
	v_addc_co_u32_e32 v33, vcc, 0, v33, vcc
	s_waitcnt vmcnt(0)
	v_fmac_f32_e32 v51, v50, v54
	global_store_dword v[32:33], v51, off
	global_load_dword v51, v83, s[58:59] offset:4
	s_waitcnt vmcnt(0)
	v_fmac_f32_e32 v51, v50, v34
	global_store_dword v[32:33], v51, off offset:4
	global_load_dword v34, v83, s[58:59] offset:8
	s_waitcnt vmcnt(0)
	v_fmac_f32_e32 v34, v50, v37
	global_store_dword v[32:33], v34, off offset:8
	global_load_dword v34, v83, s[58:59] offset:12
	s_waitcnt vmcnt(0)
	v_fmac_f32_e32 v34, v50, v35
	global_store_dword v[32:33], v34, off offset:12
	global_load_dword v34, v83, s[58:59] offset:16
	s_waitcnt lgkmcnt(3)
	v_add_f32_e32 v35, v36, v41
	s_waitcnt vmcnt(0)
	v_fmac_f32_e32 v34, v50, v35
	global_store_dword v[32:33], v34, off offset:16
	global_load_dword v34, v83, s[58:59] offset:20
	s_waitcnt lgkmcnt(2)
	v_add_f32_e32 v35, v46, v47
	s_waitcnt vmcnt(0)
	v_fmac_f32_e32 v34, v50, v35
	global_store_dword v[32:33], v34, off offset:20
	global_load_dword v34, v83, s[58:59] offset:24
	s_waitcnt lgkmcnt(1)
	v_add_f32_e32 v35, v44, v45
	s_waitcnt vmcnt(0)
	v_fmac_f32_e32 v34, v50, v35
	global_store_dword v[32:33], v34, off offset:24
	global_load_dword v34, v83, s[58:59] offset:28
	s_waitcnt lgkmcnt(0)
	v_add_f32_e32 v35, v42, v43
	s_waitcnt vmcnt(0)
	v_fmac_f32_e32 v34, v50, v35
	global_store_dword v[32:33], v34, off offset:28

.LBB0_211:
	s_or_b64 exec, exec, s[8:9]
	s_waitcnt vmcnt(19)
	v_mul_f32_e32 v34, v29, v29
	v_mul_f32_e32 v35, v31, v31
	v_fmac_f32_e32 v34, v28, v28
	v_fmac_f32_e32 v35, v30, v30
	v_ashrrev_i32_e32 v91, 31, v90
	v_add_f32_e32 v36, v34, v35
	v_and_b32_sdwa v35, v28, v118 dst_sel:DWORD dst_unused:UNUSED_PAD src0_sel:WORD_1 src1_sel:DWORD
	s_waitcnt lgkmcnt(7)
	v_cndmask_b32_e64 v33, v91, 0, s[6:7]
	v_cndmask_b32_e64 v32, v90, v98, s[6:7]
	v_add3_u32 v37, v28, v35, s75
	v_and_b32_sdwa v35, v31, v118 dst_sel:DWORD dst_unused:UNUSED_PAD src0_sel:WORD_1 src1_sel:DWORD
	s_waitcnt lgkmcnt(4)
	v_and_b32_sdwa v38, v29, v118 dst_sel:DWORD dst_unused:UNUSED_PAD src0_sel:WORD_1 src1_sel:DWORD
	v_lshlrev_b64 v[32:33], 11, v[32:33]
	v_and_b32_sdwa v34, v30, v118 dst_sel:DWORD dst_unused:UNUSED_PAD src0_sel:WORD_1 src1_sel:DWORD
	v_add3_u32 v35, v31, v35, s75
	v_add3_u32 v38, v29, v38, s75
	v_lshl_add_u64 v[32:33], v[48:49], 0, v[32:33]
	v_add3_u32 v34, v30, v34, s75
	v_and_b32_e32 v35, 0xffff0000, v35
	v_and_b32_e32 v38, 0xffff0000, v38
	v_mov_b32_e32 v95, v83
	v_or_b32_sdwa v35, v35, v34 dst_sel:DWORD dst_unused:UNUSED_PAD src0_sel:DWORD src1_sel:WORD_1
	v_or_b32_sdwa v34, v38, v37 dst_sel:DWORD dst_unused:UNUSED_PAD src0_sel:DWORD src1_sel:WORD_1
	v_lshl_add_u64 v[32:33], v[32:33], 0, v[94:95]
	global_store_dwordx2 v[32:33], v[34:35], off
	s_waitcnt vmcnt(19)
	v_mul_f32_e32 v34, v25, v25
	v_mul_f32_e32 v35, v27, v27
	v_fmac_f32_e32 v34, v24, v24
	v_fmac_f32_e32 v35, v26, v26
	v_add_f32_e32 v34, v34, v35
	v_and_b32_sdwa v35, v24, v118 dst_sel:DWORD dst_unused:UNUSED_PAD src0_sel:WORD_1 src1_sel:DWORD
	v_add3_u32 v37, v24, v35, s75
	v_and_b32_sdwa v35, v27, v118 dst_sel:DWORD dst_unused:UNUSED_PAD src0_sel:WORD_1 src1_sel:DWORD
	v_and_b32_sdwa v38, v25, v118 dst_sel:DWORD dst_unused:UNUSED_PAD src0_sel:WORD_1 src1_sel:DWORD
	v_add_f32_e32 v36, v36, v34
	v_and_b32_sdwa v34, v26, v118 dst_sel:DWORD dst_unused:UNUSED_PAD src0_sel:WORD_1 src1_sel:DWORD
	v_add3_u32 v35, v27, v35, s75
	v_add3_u32 v38, v25, v38, s75
	v_add3_u32 v34, v26, v34, s75
	v_and_b32_e32 v35, 0xffff0000, v35
	v_and_b32_e32 v38, 0xffff0000, v38
	v_or_b32_sdwa v35, v35, v34 dst_sel:DWORD dst_unused:UNUSED_PAD src0_sel:DWORD src1_sel:WORD_1
	v_or_b32_sdwa v34, v38, v37 dst_sel:DWORD dst_unused:UNUSED_PAD src0_sel:DWORD src1_sel:WORD_1
	global_store_dwordx2 v[32:33], v[34:35], off offset:512
	s_waitcnt vmcnt(19)
	v_mul_f32_e32 v34, v21, v21
	v_mul_f32_e32 v35, v23, v23
	v_fmac_f32_e32 v34, v20, v20
	v_fmac_f32_e32 v35, v22, v22
	s_waitcnt vmcnt(18)
	v_mul_f32_e32 v37, v17, v17
	v_mul_f32_e32 v38, v19, v19
	v_add_f32_e32 v34, v34, v35
	v_fmac_f32_e32 v37, v16, v16
	v_fmac_f32_e32 v38, v18, v18
	v_add_f32_e32 v34, v36, v34
	v_add_f32_e32 v37, v37, v38
	v_add_f32_e32 v34, v34, v37
	ds_bpermute_b32 v37, v111, v34
	v_and_b32_sdwa v38, v23, v118 dst_sel:DWORD dst_unused:UNUSED_PAD src0_sel:WORD_1 src1_sel:DWORD
	v_and_b32_sdwa v39, v21, v118 dst_sel:DWORD dst_unused:UNUSED_PAD src0_sel:WORD_1 src1_sel:DWORD
	v_and_b32_sdwa v35, v22, v118 dst_sel:DWORD dst_unused:UNUSED_PAD src0_sel:WORD_1 src1_sel:DWORD
	v_and_b32_sdwa v36, v20, v118 dst_sel:DWORD dst_unused:UNUSED_PAD src0_sel:WORD_1 src1_sel:DWORD
	s_waitcnt lgkmcnt(0)
	v_add_f32_e32 v34, v34, v37
	ds_bpermute_b32 v37, v112, v34
	v_add3_u32 v38, v23, v38, s75
	v_add3_u32 v39, v21, v39, s75
	v_add3_u32 v36, v20, v36, s75
	v_add3_u32 v35, v22, v35, s75
	s_waitcnt lgkmcnt(0)
	v_add_f32_e32 v37, v34, v37
	ds_bpermute_b32 v40, v113, v37
	v_and_b32_e32 v38, 0xffff0000, v38
	v_and_b32_e32 v39, 0xffff0000, v39
	v_or_b32_sdwa v35, v38, v35 dst_sel:DWORD dst_unused:UNUSED_PAD src0_sel:DWORD src1_sel:WORD_1
	v_or_b32_sdwa v34, v39, v36 dst_sel:DWORD dst_unused:UNUSED_PAD src0_sel:DWORD src1_sel:WORD_1
	global_store_dwordx2 v[32:33], v[34:35], off offset:1024
	s_waitcnt lgkmcnt(0)
	v_add_f32_e32 v35, v37, v40
	ds_bpermute_b32 v36, v114, v35
	v_and_b32_sdwa v38, v19, v118 dst_sel:DWORD dst_unused:UNUSED_PAD src0_sel:WORD_1 src1_sel:DWORD
	v_and_b32_sdwa v39, v17, v118 dst_sel:DWORD dst_unused:UNUSED_PAD src0_sel:WORD_1 src1_sel:DWORD
	v_and_b32_sdwa v34, v18, v118 dst_sel:DWORD dst_unused:UNUSED_PAD src0_sel:WORD_1 src1_sel:DWORD
	v_and_b32_sdwa v37, v16, v118 dst_sel:DWORD dst_unused:UNUSED_PAD src0_sel:WORD_1 src1_sel:DWORD
	s_waitcnt lgkmcnt(0)
	v_add_f32_e32 v35, v35, v36
	ds_bpermute_b32 v36, v115, v35
	v_add3_u32 v38, v19, v38, s75
	v_add3_u32 v39, v17, v39, s75
	v_add3_u32 v37, v16, v37, s75
	v_add3_u32 v34, v18, v34, s75
	s_waitcnt lgkmcnt(0)
	v_add_f32_e32 v36, v35, v36
	ds_bpermute_b32 v40, v116, v36
	v_and_b32_e32 v38, 0xffff0000, v38
	v_and_b32_e32 v39, 0xffff0000, v39
	v_or_b32_sdwa v35, v38, v34 dst_sel:DWORD dst_unused:UNUSED_PAD src0_sel:DWORD src1_sel:WORD_1
	v_or_b32_sdwa v34, v39, v37 dst_sel:DWORD dst_unused:UNUSED_PAD src0_sel:DWORD src1_sel:WORD_1
	global_store_dwordx2 v[32:33], v[34:35], off offset:1536
	s_waitcnt lgkmcnt(0)
	v_add_f32_e32 v32, v36, v40
	s_and_saveexec_b64 s[8:9], s[4:5]
	s_xor_b64 s[8:9], exec, s[8:9]
	s_cbranch_execz .LBB0_215
	ds_read_b128 v[34:37], v110
	ds_read_b128 v[38:41], v110 offset:16
	ds_read_b128 v[42:45], v110 offset:32
	ds_read_b128 v[50:53], v110 offset:48
	s_waitcnt lgkmcnt(3)
	v_fma_f32 v33, v28, v34, 0
	v_fma_f32 v46, v28, v35, 0
	v_fma_f32 v47, v28, v36, 0
	v_fma_f32 v54, v28, v37, 0
	s_waitcnt lgkmcnt(2)
	v_fma_f32 v55, v28, v38, 0
	v_fma_f32 v56, v28, v39, 0
	v_fma_f32 v57, v28, v40, 0
	v_fma_f32 v58, v28, v41, 0
	ds_read_b128 v[34:37], v110 offset:64
	ds_read_b128 v[38:41], v110 offset:80
	s_waitcnt lgkmcnt(3)
	v_fmac_f32_e32 v33, v29, v42
	v_fmac_f32_e32 v46, v29, v43
	v_fmac_f32_e32 v47, v29, v44
	v_fmac_f32_e32 v54, v29, v45
	s_waitcnt lgkmcnt(2)
	v_fmac_f32_e32 v55, v29, v50
	v_fmac_f32_e32 v56, v29, v51
	v_fmac_f32_e32 v57, v29, v52
	v_fmac_f32_e32 v58, v29, v53
	s_waitcnt lgkmcnt(1)
	v_fmac_f32_e32 v33, v30, v34
	v_fmac_f32_e32 v46, v30, v35
	v_fmac_f32_e32 v47, v30, v36
	v_fmac_f32_e32 v54, v30, v37
	s_waitcnt lgkmcnt(0)
	v_fmac_f32_e32 v55, v30, v38
	ds_read_b128 v[34:37], v110 offset:96
	v_fmac_f32_e32 v56, v30, v39
	v_fmac_f32_e32 v57, v30, v40
	v_fmac_f32_e32 v58, v30, v41
	ds_read_b128 v[38:41], v110 offset:112
	s_waitcnt lgkmcnt(1)
	v_fmac_f32_e32 v33, v31, v34
	v_fmac_f32_e32 v46, v31, v35
	v_fmac_f32_e32 v47, v31, v36
	v_fmac_f32_e32 v54, v31, v37
	s_waitcnt lgkmcnt(0)
	v_fmac_f32_e32 v55, v31, v38
	ds_read_b128 v[34:37], v110 offset:9216
	v_fmac_f32_e32 v56, v31, v39
	v_fmac_f32_e32 v57, v31, v40
	v_fmac_f32_e32 v58, v31, v41
	ds_read_b128 v[28:31], v110 offset:9232
	s_waitcnt lgkmcnt(1)
	v_fmac_f32_e32 v33, v24, v34
	v_fmac_f32_e32 v46, v24, v35
	v_fmac_f32_e32 v47, v24, v36
	v_fmac_f32_e32 v54, v24, v37
	s_waitcnt lgkmcnt(0)
	v_fmac_f32_e32 v55, v24, v28
	ds_read_b128 v[34:37], v110 offset:9248
	v_fmac_f32_e32 v56, v24, v29
	v_fmac_f32_e32 v57, v24, v30
	v_fmac_f32_e32 v58, v24, v31
	ds_read_b128 v[28:31], v110 offset:9264
	s_waitcnt lgkmcnt(1)
	v_fmac_f32_e32 v33, v25, v34
	v_fmac_f32_e32 v46, v25, v35
	v_fmac_f32_e32 v47, v25, v36
	v_fmac_f32_e32 v54, v25, v37
	s_waitcnt lgkmcnt(0)
	v_fmac_f32_e32 v55, v25, v28
	ds_read_b128 v[34:37], v110 offset:9280
	v_fmac_f32_e32 v56, v25, v29
	v_fmac_f32_e32 v57, v25, v30
	v_fmac_f32_e32 v58, v25, v31
	ds_read_b128 v[28:31], v110 offset:9296
	s_waitcnt lgkmcnt(1)
	v_fmac_f32_e32 v33, v26, v34
	v_fmac_f32_e32 v46, v26, v35
	v_fmac_f32_e32 v47, v26, v36
	v_fmac_f32_e32 v54, v26, v37
	s_waitcnt lgkmcnt(0)
	v_fmac_f32_e32 v55, v26, v28
	ds_read_b128 v[34:37], v110 offset:9312
	v_fmac_f32_e32 v56, v26, v29
	v_fmac_f32_e32 v57, v26, v30
	v_fmac_f32_e32 v58, v26, v31
	ds_read_b128 v[28:31], v110 offset:9328
	s_waitcnt lgkmcnt(1)
	v_fmac_f32_e32 v33, v27, v34
	v_fmac_f32_e32 v46, v27, v35
	v_fmac_f32_e32 v47, v27, v36
	v_fmac_f32_e32 v54, v27, v37
	s_waitcnt lgkmcnt(0)
	v_fmac_f32_e32 v55, v27, v28
	ds_read_b128 v[34:37], v110 offset:18432
	v_fmac_f32_e32 v56, v27, v29
	v_fmac_f32_e32 v57, v27, v30
	v_fmac_f32_e32 v58, v27, v31
	ds_read_b128 v[24:27], v110 offset:18448
	ds_read_b128 v[28:31], v110 offset:18464
	s_waitcnt lgkmcnt(2)
	v_fmac_f32_e32 v33, v20, v34
	v_fmac_f32_e32 v46, v20, v35
	v_fmac_f32_e32 v47, v20, v36
	s_waitcnt lgkmcnt(1)
	v_fmac_f32_e32 v55, v20, v24
	v_fmac_f32_e32 v56, v20, v25
	v_fmac_f32_e32 v57, v20, v26
	v_fmac_f32_e32 v58, v20, v27
	ds_read_b128 v[24:27], v110 offset:18480
	v_fmac_f32_e32 v54, v20, v37
	s_waitcnt lgkmcnt(1)
	v_fmac_f32_e32 v33, v21, v28
	v_fmac_f32_e32 v46, v21, v29
	v_fmac_f32_e32 v47, v21, v30
	v_fmac_f32_e32 v54, v21, v31
	s_waitcnt lgkmcnt(0)
	v_fmac_f32_e32 v55, v21, v24
	ds_read_b128 v[28:31], v110 offset:18496
	v_fmac_f32_e32 v56, v21, v25
	v_fmac_f32_e32 v57, v21, v26
	v_fmac_f32_e32 v58, v21, v27
	ds_read_b128 v[24:27], v110 offset:18512
	s_waitcnt lgkmcnt(1)
	v_fmac_f32_e32 v33, v22, v28
	v_fmac_f32_e32 v46, v22, v29
	v_fmac_f32_e32 v47, v22, v30
	v_fmac_f32_e32 v54, v22, v31
	s_waitcnt lgkmcnt(0)
	v_fmac_f32_e32 v55, v22, v24
	ds_read_b128 v[28:31], v110 offset:18528
	v_fmac_f32_e32 v56, v22, v25
	v_fmac_f32_e32 v57, v22, v26
	v_fmac_f32_e32 v58, v22, v27
	ds_read_b128 v[24:27], v110 offset:18544
	s_waitcnt lgkmcnt(1)
	v_fmac_f32_e32 v33, v23, v28
	v_fmac_f32_e32 v46, v23, v29
	v_fmac_f32_e32 v47, v23, v30
	v_fmac_f32_e32 v54, v23, v31
	s_waitcnt lgkmcnt(0)
	v_fmac_f32_e32 v55, v23, v24
	ds_read_b128 v[28:31], v110 offset:27648
	v_fmac_f32_e32 v56, v23, v25
	v_fmac_f32_e32 v57, v23, v26
	v_fmac_f32_e32 v58, v23, v27
	ds_read_b128 v[20:23], v110 offset:27664
	ds_read_b128 v[24:27], v110 offset:27680
	s_waitcnt lgkmcnt(2)
	v_fmac_f32_e32 v33, v16, v28
	v_fmac_f32_e32 v46, v16, v29
	v_fmac_f32_e32 v47, v16, v30
	s_waitcnt lgkmcnt(1)
	v_fmac_f32_e32 v55, v16, v20
	v_fmac_f32_e32 v56, v16, v21
	v_fmac_f32_e32 v57, v16, v22
	v_fmac_f32_e32 v58, v16, v23
	ds_read_b128 v[20:23], v110 offset:27696
	v_fmac_f32_e32 v54, v16, v31
	s_waitcnt lgkmcnt(1)
	v_fmac_f32_e32 v33, v17, v24
	v_fmac_f32_e32 v46, v17, v25
	v_fmac_f32_e32 v47, v17, v26
	v_fmac_f32_e32 v54, v17, v27
	ds_read_b128 v[24:27], v110 offset:27712
	ds_read_b128 v[28:31], v110 offset:27744
	s_waitcnt lgkmcnt(2)
	v_fmac_f32_e32 v55, v17, v20
	v_fmac_f32_e32 v56, v17, v21
	v_fmac_f32_e32 v57, v17, v22
	v_fmac_f32_e32 v58, v17, v23
	ds_read_b128 v[20:23], v110 offset:27728
	s_waitcnt lgkmcnt(2)
	v_fmac_f32_e32 v46, v18, v25
	v_fmac_f32_e32 v33, v18, v24
	v_fmac_f32_e32 v47, v18, v26
	v_fmac_f32_e32 v54, v18, v27
	ds_read_b128 v[24:27], v110 offset:27760
	s_waitcnt lgkmcnt(2)
	v_fmac_f32_e32 v46, v19, v29
	s_waitcnt lgkmcnt(1)
	v_fmac_f32_e32 v55, v18, v20
	v_fmac_f32_e32 v56, v18, v21
	v_fmac_f32_e32 v57, v18, v22
	v_fmac_f32_e32 v58, v18, v23
	ds_bpermute_b32 v18, v111, v46
	v_fmac_f32_e32 v47, v19, v30
	v_fmac_f32_e32 v33, v19, v28
	v_fmac_f32_e32 v54, v19, v31
	s_waitcnt lgkmcnt(1)
	v_fmac_f32_e32 v55, v19, v24
	s_waitcnt lgkmcnt(0)
	v_add_f32_e32 v18, v46, v18
	ds_bpermute_b32 v20, v112, v18
	v_fmac_f32_e32 v56, v19, v25
	v_fmac_f32_e32 v57, v19, v26
	v_fmac_f32_e32 v58, v19, v27
	ds_bpermute_b32 v19, v111, v47
	s_waitcnt lgkmcnt(1)
	v_add_f32_e32 v18, v18, v20
	ds_bpermute_b32 v20, v113, v18
	ds_bpermute_b32 v22, v111, v55
	ds_bpermute_b32 v16, v111, v33
	s_waitcnt lgkmcnt(3)
	v_add_f32_e32 v19, v47, v19
	ds_bpermute_b32 v21, v112, v19
	s_waitcnt lgkmcnt(3)
	v_add_f32_e32 v18, v18, v20
	ds_bpermute_b32 v20, v114, v18
	ds_bpermute_b32 v28, v111, v58
	s_waitcnt lgkmcnt(3)
	v_add_f32_e32 v16, v33, v16
	s_waitcnt lgkmcnt(2)
	v_add_f32_e32 v19, v19, v21
	ds_bpermute_b32 v21, v113, v19
	s_waitcnt lgkmcnt(2)
	v_add_f32_e32 v18, v18, v20
	ds_bpermute_b32 v20, v111, v54
	s_waitcnt lgkmcnt(2)
	v_add_f32_e32 v28, v58, v28
	ds_bpermute_b32 v17, v112, v16
	s_waitcnt lgkmcnt(2)
	v_add_f32_e32 v19, v19, v21
	v_add_f32_e32 v21, v55, v22
	s_waitcnt lgkmcnt(1)
	v_add_f32_e32 v20, v54, v20
	ds_bpermute_b32 v24, v112, v20
	ds_bpermute_b32 v22, v112, v21
	ds_bpermute_b32 v25, v114, v19
	ds_bpermute_b32 v31, v112, v28
	s_waitcnt lgkmcnt(4)
	v_add_f32_e32 v16, v16, v17
	s_waitcnt lgkmcnt(3)
	v_add_f32_e32 v20, v20, v24
	s_waitcnt lgkmcnt(2)
	v_add_f32_e32 v21, v21, v22
	ds_bpermute_b32 v24, v113, v20
	ds_bpermute_b32 v22, v113, v21
	s_waitcnt lgkmcnt(3)
	v_add_f32_e32 v19, v19, v25
	ds_bpermute_b32 v25, v115, v19
	s_waitcnt lgkmcnt(3)
	v_add_f32_e32 v28, v28, v31
	s_waitcnt lgkmcnt(2)
	v_add_f32_e32 v20, v20, v24
	s_waitcnt lgkmcnt(1)
	v_add_f32_e32 v22, v21, v22
	ds_bpermute_b32 v24, v114, v20
	ds_bpermute_b32 v26, v114, v22
	s_waitcnt lgkmcnt(2)
	v_add_f32_e32 v21, v19, v25
	ds_bpermute_b32 v17, v113, v16
	ds_bpermute_b32 v31, v113, v28
	s_waitcnt lgkmcnt(3)
	v_add_f32_e32 v20, v20, v24
	s_waitcnt lgkmcnt(2)
	v_add_f32_e32 v25, v22, v26
	ds_bpermute_b32 v27, v115, v20
	ds_bpermute_b32 v26, v115, v25
	s_waitcnt lgkmcnt(3)
	v_add_f32_e32 v16, v16, v17
	s_waitcnt lgkmcnt(2)
	v_add_f32_e32 v28, v28, v31
	ds_bpermute_b32 v17, v114, v16
	s_waitcnt lgkmcnt(2)
	v_add_f32_e32 v19, v20, v27
	ds_bpermute_b32 v27, v111, v56
	s_waitcnt lgkmcnt(2)
	v_add_f32_e32 v20, v25, v26
	ds_bpermute_b32 v26, v111, v57
	ds_bpermute_b32 v31, v114, v28
	s_waitcnt lgkmcnt(3)
	v_add_f32_e32 v16, v16, v17
	s_waitcnt lgkmcnt(2)
	v_add_f32_e32 v27, v56, v27
	ds_bpermute_b32 v29, v112, v27
	s_waitcnt lgkmcnt(2)
	v_add_f32_e32 v26, v57, v26
	ds_bpermute_b32 v30, v112, v26
	s_waitcnt lgkmcnt(2)
	v_add_f32_e32 v34, v28, v31
	ds_bpermute_b32 v17, v115, v16
	s_waitcnt lgkmcnt(2)
	v_add_f32_e32 v27, v27, v29
	ds_bpermute_b32 v29, v113, v27
	s_waitcnt lgkmcnt(2)
	v_add_f32_e32 v26, v26, v30
	ds_bpermute_b32 v30, v113, v26
	ds_bpermute_b32 v23, v115, v18
	ds_bpermute_b32 v35, v115, v34
	s_waitcnt lgkmcnt(3)
	v_add_f32_e32 v27, v27, v29
	ds_bpermute_b32 v29, v114, v27
	s_waitcnt lgkmcnt(3)
	v_add_f32_e32 v26, v26, v30
	ds_bpermute_b32 v30, v114, v26
	v_add_f32_e32 v16, v16, v17
	s_waitcnt lgkmcnt(3)
	v_add_f32_e32 v18, v18, v23
	s_waitcnt lgkmcnt(1)
	v_add_f32_e32 v27, v27, v29
	ds_bpermute_b32 v29, v115, v27
	s_waitcnt lgkmcnt(1)
	v_add_f32_e32 v26, v26, v30
	ds_bpermute_b32 v33, v115, v26
	ds_bpermute_b32 v17, v116, v16
	ds_bpermute_b32 v23, v116, v18
	s_waitcnt lgkmcnt(3)
	v_add_f32_e32 v30, v27, v29
	ds_bpermute_b32 v24, v116, v21
	s_waitcnt lgkmcnt(3)
	v_add_f32_e32 v28, v26, v33
	v_add_f32_e32 v26, v34, v35
	ds_bpermute_b32 v22, v116, v19
	ds_bpermute_b32 v25, v116, v20
	ds_bpermute_b32 v31, v116, v30
	ds_bpermute_b32 v29, v116, v28
	ds_bpermute_b32 v27, v116, v26
	s_and_saveexec_b64 s[10:11], s[2:3]
	s_cbranch_execz .LBB0_214
	v_lshl_add_u64 v[34:35], v[90:91], 2, s[12:13]
	global_store_dword v[34:35], v32, off
	global_load_dword v33, v83, s[58:59]
	v_fmamk_f32 v32, v32, 0x3a800000, v117
	v_mul_f32_e32 v36, 0x4b800000, v32
	v_cmp_gt_f32_e32 vcc, s76, v32
	s_waitcnt lgkmcnt(6)
	v_add_f32_e32 v18, v18, v23
	s_waitcnt lgkmcnt(5)
	v_add_f32_e32 v21, v21, v24
	v_cndmask_b32_e32 v32, v32, v36, vcc
	v_rsq_f32_e32 v32, v32
	v_add_f32_e32 v36, v16, v17
	v_mad_i64_i32 v[16:17], s[14:15], v90, 28, v[34:35]
	v_mul_f32_e32 v34, 0x45800000, v32
	v_cndmask_b32_e32 v32, v32, v34, vcc
	v_add_co_u32_e32 v16, vcc, s77, v16
	s_waitcnt lgkmcnt(4)
	v_add_f32_e32 v19, v19, v22
	v_addc_co_u32_e32 v17, vcc, 0, v17, vcc
	s_waitcnt vmcnt(0)
	v_fmac_f32_e32 v33, v32, v36
	global_store_dword v[16:17], v33, off
	global_load_dword v33, v83, s[58:59] offset:4
	s_waitcnt vmcnt(0)
	v_fmac_f32_e32 v33, v32, v18
	global_store_dword v[16:17], v33, off offset:4
	global_load_dword v18, v83, s[58:59] offset:8
	s_waitcnt vmcnt(0)
	v_fmac_f32_e32 v18, v32, v21
	global_store_dword v[16:17], v18, off offset:8
	global_load_dword v18, v83, s[58:59] offset:12
	s_waitcnt vmcnt(0)
	v_fmac_f32_e32 v18, v32, v19
	global_store_dword v[16:17], v18, off offset:12
	global_load_dword v18, v83, s[58:59] offset:16
	s_waitcnt lgkmcnt(3)
	v_add_f32_e32 v19, v20, v25
	s_waitcnt vmcnt(0)
	v_fmac_f32_e32 v18, v32, v19
	global_store_dword v[16:17], v18, off offset:16
	global_load_dword v18, v83, s[58:59] offset:20
	s_waitcnt lgkmcnt(2)
	v_add_f32_e32 v19, v30, v31
	s_waitcnt vmcnt(0)
	v_fmac_f32_e32 v18, v32, v19
	global_store_dword v[16:17], v18, off offset:20
	global_load_dword v18, v83, s[58:59] offset:24
	s_waitcnt lgkmcnt(1)
	v_add_f32_e32 v19, v28, v29
	s_waitcnt vmcnt(0)
	v_fmac_f32_e32 v18, v32, v19
	global_store_dword v[16:17], v18, off offset:24
	global_load_dword v18, v83, s[58:59] offset:28
	s_waitcnt lgkmcnt(0)
	v_add_f32_e32 v19, v26, v27
	s_waitcnt vmcnt(0)
	v_fmac_f32_e32 v18, v32, v19
	global_store_dword v[16:17], v18, off offset:28

.LBB0_219:
	s_or_b64 exec, exec, s[8:9]
	s_waitcnt vmcnt(19)
	v_mul_f32_e32 v18, v13, v13
	v_mul_f32_e32 v19, v15, v15
	v_fmac_f32_e32 v18, v12, v12
	v_fmac_f32_e32 v19, v14, v14
	v_ashrrev_i32_e32 v89, 31, v88
	v_add_f32_e32 v20, v18, v19
	v_and_b32_sdwa v19, v12, v118 dst_sel:DWORD dst_unused:UNUSED_PAD src0_sel:WORD_1 src1_sel:DWORD
	s_waitcnt lgkmcnt(7)
	v_cndmask_b32_e64 v17, v89, 0, s[6:7]
	v_cndmask_b32_e64 v16, v88, v92, s[6:7]
	v_add3_u32 v21, v12, v19, s75
	v_and_b32_sdwa v19, v15, v118 dst_sel:DWORD dst_unused:UNUSED_PAD src0_sel:WORD_1 src1_sel:DWORD
	s_waitcnt lgkmcnt(4)
	v_and_b32_sdwa v22, v13, v118 dst_sel:DWORD dst_unused:UNUSED_PAD src0_sel:WORD_1 src1_sel:DWORD
	v_lshlrev_b64 v[16:17], 11, v[16:17]
	v_and_b32_sdwa v18, v14, v118 dst_sel:DWORD dst_unused:UNUSED_PAD src0_sel:WORD_1 src1_sel:DWORD
	v_add3_u32 v19, v15, v19, s75
	v_add3_u32 v22, v13, v22, s75
	v_lshl_add_u64 v[16:17], v[48:49], 0, v[16:17]
	v_add3_u32 v18, v14, v18, s75
	v_and_b32_e32 v19, 0xffff0000, v19
	v_and_b32_e32 v22, 0xffff0000, v22
	v_mov_b32_e32 v95, v83
	v_or_b32_sdwa v19, v19, v18 dst_sel:DWORD dst_unused:UNUSED_PAD src0_sel:DWORD src1_sel:WORD_1
	v_or_b32_sdwa v18, v22, v21 dst_sel:DWORD dst_unused:UNUSED_PAD src0_sel:DWORD src1_sel:WORD_1
	v_lshl_add_u64 v[16:17], v[16:17], 0, v[94:95]
	global_store_dwordx2 v[16:17], v[18:19], off
	s_waitcnt vmcnt(19)
	v_mul_f32_e32 v18, v9, v9
	v_mul_f32_e32 v19, v11, v11
	v_fmac_f32_e32 v18, v8, v8
	v_fmac_f32_e32 v19, v10, v10
	v_add_f32_e32 v18, v18, v19
	v_and_b32_sdwa v19, v8, v118 dst_sel:DWORD dst_unused:UNUSED_PAD src0_sel:WORD_1 src1_sel:DWORD
	v_add3_u32 v21, v8, v19, s75
	v_and_b32_sdwa v19, v11, v118 dst_sel:DWORD dst_unused:UNUSED_PAD src0_sel:WORD_1 src1_sel:DWORD
	v_and_b32_sdwa v22, v9, v118 dst_sel:DWORD dst_unused:UNUSED_PAD src0_sel:WORD_1 src1_sel:DWORD
	v_add_f32_e32 v20, v20, v18
	v_and_b32_sdwa v18, v10, v118 dst_sel:DWORD dst_unused:UNUSED_PAD src0_sel:WORD_1 src1_sel:DWORD
	v_add3_u32 v19, v11, v19, s75
	v_add3_u32 v22, v9, v22, s75
	v_add3_u32 v18, v10, v18, s75
	v_and_b32_e32 v19, 0xffff0000, v19
	v_and_b32_e32 v22, 0xffff0000, v22
	v_or_b32_sdwa v19, v19, v18 dst_sel:DWORD dst_unused:UNUSED_PAD src0_sel:DWORD src1_sel:WORD_1
	v_or_b32_sdwa v18, v22, v21 dst_sel:DWORD dst_unused:UNUSED_PAD src0_sel:DWORD src1_sel:WORD_1
	global_store_dwordx2 v[16:17], v[18:19], off offset:512
	s_waitcnt vmcnt(19)
	v_mul_f32_e32 v18, v5, v5
	v_mul_f32_e32 v19, v7, v7
	v_fmac_f32_e32 v18, v4, v4
	v_fmac_f32_e32 v19, v6, v6
	s_waitcnt vmcnt(18)
	v_mul_f32_e32 v21, v1, v1
	v_mul_f32_e32 v22, v3, v3
	v_add_f32_e32 v18, v18, v19
	v_fmac_f32_e32 v21, v0, v0
	v_fmac_f32_e32 v22, v2, v2
	v_add_f32_e32 v18, v20, v18
	v_add_f32_e32 v21, v21, v22
	v_add_f32_e32 v18, v18, v21
	ds_bpermute_b32 v21, v111, v18
	v_and_b32_sdwa v22, v7, v118 dst_sel:DWORD dst_unused:UNUSED_PAD src0_sel:WORD_1 src1_sel:DWORD
	v_and_b32_sdwa v23, v5, v118 dst_sel:DWORD dst_unused:UNUSED_PAD src0_sel:WORD_1 src1_sel:DWORD
	v_and_b32_sdwa v19, v6, v118 dst_sel:DWORD dst_unused:UNUSED_PAD src0_sel:WORD_1 src1_sel:DWORD
	v_and_b32_sdwa v20, v4, v118 dst_sel:DWORD dst_unused:UNUSED_PAD src0_sel:WORD_1 src1_sel:DWORD
	s_waitcnt lgkmcnt(0)
	v_add_f32_e32 v18, v18, v21
	ds_bpermute_b32 v21, v112, v18
	v_add3_u32 v22, v7, v22, s75
	v_add3_u32 v23, v5, v23, s75
	v_add3_u32 v20, v4, v20, s75
	v_add3_u32 v19, v6, v19, s75
	s_waitcnt lgkmcnt(0)
	v_add_f32_e32 v21, v18, v21
	ds_bpermute_b32 v24, v113, v21
	v_and_b32_e32 v22, 0xffff0000, v22
	v_and_b32_e32 v23, 0xffff0000, v23
	v_or_b32_sdwa v19, v22, v19 dst_sel:DWORD dst_unused:UNUSED_PAD src0_sel:DWORD src1_sel:WORD_1
	v_or_b32_sdwa v18, v23, v20 dst_sel:DWORD dst_unused:UNUSED_PAD src0_sel:DWORD src1_sel:WORD_1
	global_store_dwordx2 v[16:17], v[18:19], off offset:1024
	s_waitcnt lgkmcnt(0)
	v_add_f32_e32 v19, v21, v24
	ds_bpermute_b32 v20, v114, v19
	v_and_b32_sdwa v22, v3, v118 dst_sel:DWORD dst_unused:UNUSED_PAD src0_sel:WORD_1 src1_sel:DWORD
	v_and_b32_sdwa v23, v1, v118 dst_sel:DWORD dst_unused:UNUSED_PAD src0_sel:WORD_1 src1_sel:DWORD
	v_and_b32_sdwa v18, v2, v118 dst_sel:DWORD dst_unused:UNUSED_PAD src0_sel:WORD_1 src1_sel:DWORD
	v_and_b32_sdwa v21, v0, v118 dst_sel:DWORD dst_unused:UNUSED_PAD src0_sel:WORD_1 src1_sel:DWORD
	s_waitcnt lgkmcnt(0)
	v_add_f32_e32 v19, v19, v20
	ds_bpermute_b32 v20, v115, v19
	v_add3_u32 v22, v3, v22, s75
	v_add3_u32 v23, v1, v23, s75
	v_add3_u32 v21, v0, v21, s75
	v_add3_u32 v18, v2, v18, s75
	s_waitcnt lgkmcnt(0)
	v_add_f32_e32 v20, v19, v20
	ds_bpermute_b32 v24, v116, v20
	v_and_b32_e32 v22, 0xffff0000, v22
	v_and_b32_e32 v23, 0xffff0000, v23
	v_or_b32_sdwa v19, v22, v18 dst_sel:DWORD dst_unused:UNUSED_PAD src0_sel:DWORD src1_sel:WORD_1
	v_or_b32_sdwa v18, v23, v21 dst_sel:DWORD dst_unused:UNUSED_PAD src0_sel:DWORD src1_sel:WORD_1
	global_store_dwordx2 v[16:17], v[18:19], off offset:1536
	s_waitcnt lgkmcnt(0)
	v_add_f32_e32 v16, v20, v24
	s_and_saveexec_b64 s[6:7], s[4:5]
	s_xor_b64 s[4:5], exec, s[6:7]
	s_cbranch_execz .LBB0_223
	ds_read_b128 v[18:21], v110
	ds_read_b128 v[22:25], v110 offset:16
	ds_read_b128 v[26:29], v110 offset:32
	ds_read_b128 v[30:33], v110 offset:48
	s_waitcnt lgkmcnt(3)
	v_fma_f32 v17, v12, v18, 0
	v_fma_f32 v34, v12, v19, 0
	v_fma_f32 v35, v12, v20, 0
	v_fma_f32 v36, v12, v21, 0
	s_waitcnt lgkmcnt(2)
	v_fma_f32 v37, v12, v22, 0
	v_fma_f32 v38, v12, v23, 0
	v_fma_f32 v39, v12, v24, 0
	v_fma_f32 v40, v12, v25, 0
	ds_read_b128 v[18:21], v110 offset:64
	ds_read_b128 v[22:25], v110 offset:80
	s_waitcnt lgkmcnt(3)
	v_fmac_f32_e32 v17, v13, v26
	v_fmac_f32_e32 v34, v13, v27
	v_fmac_f32_e32 v35, v13, v28
	v_fmac_f32_e32 v36, v13, v29
	s_waitcnt lgkmcnt(2)
	v_fmac_f32_e32 v37, v13, v30
	v_fmac_f32_e32 v38, v13, v31
	v_fmac_f32_e32 v39, v13, v32
	v_fmac_f32_e32 v40, v13, v33
	s_waitcnt lgkmcnt(1)
	v_fmac_f32_e32 v17, v14, v18
	v_fmac_f32_e32 v34, v14, v19
	v_fmac_f32_e32 v35, v14, v20
	v_fmac_f32_e32 v36, v14, v21
	s_waitcnt lgkmcnt(0)
	v_fmac_f32_e32 v37, v14, v22
	ds_read_b128 v[18:21], v110 offset:96
	v_fmac_f32_e32 v38, v14, v23
	v_fmac_f32_e32 v39, v14, v24
	v_fmac_f32_e32 v40, v14, v25
	ds_read_b128 v[22:25], v110 offset:112
	s_waitcnt lgkmcnt(1)
	v_fmac_f32_e32 v17, v15, v18
	v_fmac_f32_e32 v34, v15, v19
	v_fmac_f32_e32 v35, v15, v20
	v_fmac_f32_e32 v36, v15, v21
	s_waitcnt lgkmcnt(0)
	v_fmac_f32_e32 v37, v15, v22
	ds_read_b128 v[18:21], v110 offset:9216
	v_fmac_f32_e32 v38, v15, v23
	v_fmac_f32_e32 v39, v15, v24
	v_fmac_f32_e32 v40, v15, v25
	ds_read_b128 v[12:15], v110 offset:9232
	s_waitcnt lgkmcnt(1)
	v_fmac_f32_e32 v17, v8, v18
	v_fmac_f32_e32 v34, v8, v19
	v_fmac_f32_e32 v35, v8, v20
	v_fmac_f32_e32 v36, v8, v21
	s_waitcnt lgkmcnt(0)
	v_fmac_f32_e32 v37, v8, v12
	ds_read_b128 v[18:21], v110 offset:9248
	v_fmac_f32_e32 v38, v8, v13
	v_fmac_f32_e32 v39, v8, v14
	v_fmac_f32_e32 v40, v8, v15
	ds_read_b128 v[12:15], v110 offset:9264
	s_waitcnt lgkmcnt(1)
	v_fmac_f32_e32 v17, v9, v18
	v_fmac_f32_e32 v34, v9, v19
	v_fmac_f32_e32 v35, v9, v20
	v_fmac_f32_e32 v36, v9, v21
	s_waitcnt lgkmcnt(0)
	v_fmac_f32_e32 v37, v9, v12
	ds_read_b128 v[18:21], v110 offset:9280
	v_fmac_f32_e32 v38, v9, v13
	v_fmac_f32_e32 v39, v9, v14
	v_fmac_f32_e32 v40, v9, v15
	ds_read_b128 v[12:15], v110 offset:9296
	s_waitcnt lgkmcnt(1)
	v_fmac_f32_e32 v17, v10, v18
	v_fmac_f32_e32 v34, v10, v19
	v_fmac_f32_e32 v35, v10, v20
	v_fmac_f32_e32 v36, v10, v21
	s_waitcnt lgkmcnt(0)
	v_fmac_f32_e32 v37, v10, v12
	ds_read_b128 v[18:21], v110 offset:9312
	v_fmac_f32_e32 v38, v10, v13
	v_fmac_f32_e32 v39, v10, v14
	v_fmac_f32_e32 v40, v10, v15
	ds_read_b128 v[12:15], v110 offset:9328
	s_waitcnt lgkmcnt(1)
	v_fmac_f32_e32 v17, v11, v18
	v_fmac_f32_e32 v34, v11, v19
	v_fmac_f32_e32 v35, v11, v20
	v_fmac_f32_e32 v36, v11, v21
	s_waitcnt lgkmcnt(0)
	v_fmac_f32_e32 v37, v11, v12
	ds_read_b128 v[18:21], v110 offset:18432
	v_fmac_f32_e32 v38, v11, v13
	v_fmac_f32_e32 v39, v11, v14
	v_fmac_f32_e32 v40, v11, v15
	ds_read_b128 v[8:11], v110 offset:18448
	ds_read_b128 v[12:15], v110 offset:18464
	s_waitcnt lgkmcnt(2)
	v_fmac_f32_e32 v17, v4, v18
	v_fmac_f32_e32 v34, v4, v19
	v_fmac_f32_e32 v35, v4, v20
	s_waitcnt lgkmcnt(1)
	v_fmac_f32_e32 v37, v4, v8
	v_fmac_f32_e32 v38, v4, v9
	v_fmac_f32_e32 v39, v4, v10
	v_fmac_f32_e32 v40, v4, v11
	ds_read_b128 v[8:11], v110 offset:18480
	v_fmac_f32_e32 v36, v4, v21
	s_waitcnt lgkmcnt(1)
	v_fmac_f32_e32 v17, v5, v12
	v_fmac_f32_e32 v34, v5, v13
	v_fmac_f32_e32 v35, v5, v14
	v_fmac_f32_e32 v36, v5, v15
	s_waitcnt lgkmcnt(0)
	v_fmac_f32_e32 v37, v5, v8
	ds_read_b128 v[12:15], v110 offset:18496
	v_fmac_f32_e32 v38, v5, v9
	v_fmac_f32_e32 v39, v5, v10
	v_fmac_f32_e32 v40, v5, v11
	ds_read_b128 v[8:11], v110 offset:18512
	s_waitcnt lgkmcnt(1)
	v_fmac_f32_e32 v17, v6, v12
	v_fmac_f32_e32 v34, v6, v13
	v_fmac_f32_e32 v35, v6, v14
	v_fmac_f32_e32 v36, v6, v15
	s_waitcnt lgkmcnt(0)
	v_fmac_f32_e32 v37, v6, v8
	ds_read_b128 v[12:15], v110 offset:18528
	v_fmac_f32_e32 v38, v6, v9
	v_fmac_f32_e32 v39, v6, v10
	v_fmac_f32_e32 v40, v6, v11
	ds_read_b128 v[8:11], v110 offset:18544
	s_waitcnt lgkmcnt(1)
	v_fmac_f32_e32 v17, v7, v12
	v_fmac_f32_e32 v34, v7, v13
	v_fmac_f32_e32 v35, v7, v14
	v_fmac_f32_e32 v36, v7, v15
	s_waitcnt lgkmcnt(0)
	v_fmac_f32_e32 v37, v7, v8
	ds_read_b128 v[12:15], v110 offset:27648
	v_fmac_f32_e32 v38, v7, v9
	v_fmac_f32_e32 v39, v7, v10
	v_fmac_f32_e32 v40, v7, v11
	ds_read_b128 v[4:7], v110 offset:27664
	ds_read_b128 v[8:11], v110 offset:27680
	s_waitcnt lgkmcnt(2)
	v_fmac_f32_e32 v17, v0, v12
	v_fmac_f32_e32 v34, v0, v13
	v_fmac_f32_e32 v35, v0, v14
	s_waitcnt lgkmcnt(1)
	v_fmac_f32_e32 v37, v0, v4
	v_fmac_f32_e32 v38, v0, v5
	v_fmac_f32_e32 v39, v0, v6
	v_fmac_f32_e32 v40, v0, v7
	ds_read_b128 v[4:7], v110 offset:27696
	v_fmac_f32_e32 v36, v0, v15
	s_waitcnt lgkmcnt(1)
	v_fmac_f32_e32 v17, v1, v8
	v_fmac_f32_e32 v34, v1, v9
	v_fmac_f32_e32 v35, v1, v10
	v_fmac_f32_e32 v36, v1, v11
	ds_read_b128 v[8:11], v110 offset:27712
	ds_read_b128 v[12:15], v110 offset:27744
	s_waitcnt lgkmcnt(2)
	v_fmac_f32_e32 v37, v1, v4
	v_fmac_f32_e32 v38, v1, v5
	v_fmac_f32_e32 v39, v1, v6
	v_fmac_f32_e32 v40, v1, v7
	ds_read_b128 v[4:7], v110 offset:27728
	s_waitcnt lgkmcnt(2)
	v_fmac_f32_e32 v34, v2, v9
	v_fmac_f32_e32 v17, v2, v8
	v_fmac_f32_e32 v35, v2, v10
	v_fmac_f32_e32 v36, v2, v11
	ds_read_b128 v[8:11], v110 offset:27760
	s_waitcnt lgkmcnt(2)
	v_fmac_f32_e32 v34, v3, v13
	s_waitcnt lgkmcnt(1)
	v_fmac_f32_e32 v37, v2, v4
	v_fmac_f32_e32 v38, v2, v5
	v_fmac_f32_e32 v39, v2, v6
	v_fmac_f32_e32 v40, v2, v7
	ds_bpermute_b32 v2, v111, v34
	v_fmac_f32_e32 v35, v3, v14
	v_fmac_f32_e32 v17, v3, v12
	v_fmac_f32_e32 v36, v3, v15
	s_waitcnt lgkmcnt(1)
	v_fmac_f32_e32 v37, v3, v8
	s_waitcnt lgkmcnt(0)
	v_add_f32_e32 v2, v34, v2
	ds_bpermute_b32 v4, v112, v2
	v_fmac_f32_e32 v38, v3, v9
	v_fmac_f32_e32 v39, v3, v10
	v_fmac_f32_e32 v40, v3, v11
	ds_bpermute_b32 v3, v111, v35
	s_waitcnt lgkmcnt(1)
	v_add_f32_e32 v2, v2, v4
	ds_bpermute_b32 v4, v113, v2
	ds_bpermute_b32 v6, v111, v37
	ds_bpermute_b32 v0, v111, v17
	s_waitcnt lgkmcnt(3)
	v_add_f32_e32 v3, v35, v3
	ds_bpermute_b32 v5, v112, v3
	s_waitcnt lgkmcnt(3)
	v_add_f32_e32 v2, v2, v4
	ds_bpermute_b32 v4, v114, v2
	ds_bpermute_b32 v12, v111, v40
	s_waitcnt lgkmcnt(3)
	v_add_f32_e32 v0, v17, v0
	s_waitcnt lgkmcnt(2)
	v_add_f32_e32 v3, v3, v5
	ds_bpermute_b32 v5, v113, v3
	s_waitcnt lgkmcnt(2)
	v_add_f32_e32 v2, v2, v4
	ds_bpermute_b32 v4, v111, v36
	s_waitcnt lgkmcnt(2)
	v_add_f32_e32 v12, v40, v12
	ds_bpermute_b32 v1, v112, v0
	s_waitcnt lgkmcnt(2)
	v_add_f32_e32 v3, v3, v5
	v_add_f32_e32 v5, v37, v6
	s_waitcnt lgkmcnt(1)
	v_add_f32_e32 v4, v36, v4
	ds_bpermute_b32 v8, v112, v4
	ds_bpermute_b32 v6, v112, v5
	ds_bpermute_b32 v9, v114, v3
	ds_bpermute_b32 v15, v112, v12
	s_waitcnt lgkmcnt(4)
	v_add_f32_e32 v0, v0, v1
	s_waitcnt lgkmcnt(3)
	v_add_f32_e32 v4, v4, v8
	s_waitcnt lgkmcnt(2)
	v_add_f32_e32 v5, v5, v6
	ds_bpermute_b32 v8, v113, v4
	ds_bpermute_b32 v6, v113, v5
	s_waitcnt lgkmcnt(3)
	v_add_f32_e32 v3, v3, v9
	ds_bpermute_b32 v9, v115, v3
	s_waitcnt lgkmcnt(3)
	v_add_f32_e32 v12, v12, v15
	s_waitcnt lgkmcnt(2)
	v_add_f32_e32 v4, v4, v8
	s_waitcnt lgkmcnt(1)
	v_add_f32_e32 v6, v5, v6
	ds_bpermute_b32 v8, v114, v4
	ds_bpermute_b32 v10, v114, v6
	s_waitcnt lgkmcnt(2)
	v_add_f32_e32 v5, v3, v9
	ds_bpermute_b32 v1, v113, v0
	ds_bpermute_b32 v15, v113, v12
	s_waitcnt lgkmcnt(3)
	v_add_f32_e32 v4, v4, v8
	s_waitcnt lgkmcnt(2)
	v_add_f32_e32 v9, v6, v10
	ds_bpermute_b32 v11, v115, v4
	ds_bpermute_b32 v10, v115, v9
	s_waitcnt lgkmcnt(3)
	v_add_f32_e32 v0, v0, v1
	s_waitcnt lgkmcnt(2)
	v_add_f32_e32 v12, v12, v15
	ds_bpermute_b32 v1, v114, v0
	s_waitcnt lgkmcnt(2)
	v_add_f32_e32 v3, v4, v11
	ds_bpermute_b32 v11, v111, v38
	s_waitcnt lgkmcnt(2)
	v_add_f32_e32 v4, v9, v10
	ds_bpermute_b32 v10, v111, v39
	ds_bpermute_b32 v15, v114, v12
	s_waitcnt lgkmcnt(3)
	v_add_f32_e32 v0, v0, v1
	s_waitcnt lgkmcnt(2)
	v_add_f32_e32 v11, v38, v11
	ds_bpermute_b32 v13, v112, v11
	s_waitcnt lgkmcnt(2)
	v_add_f32_e32 v10, v39, v10
	ds_bpermute_b32 v14, v112, v10
	s_waitcnt lgkmcnt(2)
	v_add_f32_e32 v18, v12, v15
	ds_bpermute_b32 v1, v115, v0
	s_waitcnt lgkmcnt(2)
	v_add_f32_e32 v11, v11, v13
	ds_bpermute_b32 v13, v113, v11
	s_waitcnt lgkmcnt(2)
	v_add_f32_e32 v10, v10, v14
	ds_bpermute_b32 v14, v113, v10
	ds_bpermute_b32 v7, v115, v2
	ds_bpermute_b32 v19, v115, v18
	s_waitcnt lgkmcnt(3)
	v_add_f32_e32 v11, v11, v13
	ds_bpermute_b32 v13, v114, v11
	s_waitcnt lgkmcnt(3)
	v_add_f32_e32 v10, v10, v14
	ds_bpermute_b32 v14, v114, v10
	v_add_f32_e32 v0, v0, v1
	s_waitcnt lgkmcnt(3)
	v_add_f32_e32 v2, v2, v7
	s_waitcnt lgkmcnt(1)
	v_add_f32_e32 v11, v11, v13
	ds_bpermute_b32 v13, v115, v11
	s_waitcnt lgkmcnt(1)
	v_add_f32_e32 v10, v10, v14
	ds_bpermute_b32 v17, v115, v10
	ds_bpermute_b32 v1, v116, v0
	ds_bpermute_b32 v7, v116, v2
	s_waitcnt lgkmcnt(3)
	v_add_f32_e32 v14, v11, v13
	ds_bpermute_b32 v8, v116, v5
	s_waitcnt lgkmcnt(3)
	v_add_f32_e32 v12, v10, v17
	v_add_f32_e32 v10, v18, v19
	ds_bpermute_b32 v6, v116, v3
	ds_bpermute_b32 v9, v116, v4
	ds_bpermute_b32 v15, v116, v14
	ds_bpermute_b32 v13, v116, v12
	ds_bpermute_b32 v11, v116, v10
	s_and_saveexec_b64 s[6:7], s[2:3]
	s_cbranch_execz .LBB0_222
	v_lshl_add_u64 v[18:19], v[88:89], 2, s[12:13]
	global_store_dword v[18:19], v16, off
	global_load_dword v17, v83, s[58:59]
	v_fmamk_f32 v16, v16, 0x3a800000, v117
	v_mul_f32_e32 v20, 0x4b800000, v16
	v_cmp_gt_f32_e32 vcc, s76, v16
	s_waitcnt lgkmcnt(6)
	v_add_f32_e32 v2, v2, v7
	s_waitcnt lgkmcnt(5)
	v_add_f32_e32 v5, v5, v8
	v_cndmask_b32_e32 v16, v16, v20, vcc
	v_rsq_f32_e32 v16, v16
	v_add_f32_e32 v20, v0, v1
	v_mad_i64_i32 v[0:1], s[8:9], v88, 28, v[18:19]
	v_mul_f32_e32 v18, 0x45800000, v16
	v_cndmask_b32_e32 v16, v16, v18, vcc
	v_add_co_u32_e32 v0, vcc, s77, v0
	s_waitcnt lgkmcnt(4)
	v_add_f32_e32 v3, v3, v6
	v_addc_co_u32_e32 v1, vcc, 0, v1, vcc
	s_waitcnt vmcnt(0)
	v_fmac_f32_e32 v17, v16, v20
	global_store_dword v[0:1], v17, off
	global_load_dword v17, v83, s[58:59] offset:4
	s_waitcnt vmcnt(0)
	v_fmac_f32_e32 v17, v16, v2
	global_store_dword v[0:1], v17, off offset:4
	global_load_dword v2, v83, s[58:59] offset:8
	s_waitcnt vmcnt(0)
	v_fmac_f32_e32 v2, v16, v5
	global_store_dword v[0:1], v2, off offset:8
	global_load_dword v2, v83, s[58:59] offset:12
	s_waitcnt vmcnt(0)
	v_fmac_f32_e32 v2, v16, v3
	global_store_dword v[0:1], v2, off offset:12
	global_load_dword v2, v83, s[58:59] offset:16
	s_waitcnt lgkmcnt(3)
	v_add_f32_e32 v3, v4, v9
	s_waitcnt vmcnt(0)
	v_fmac_f32_e32 v2, v16, v3
	global_store_dword v[0:1], v2, off offset:16
	global_load_dword v2, v83, s[58:59] offset:20
	s_waitcnt lgkmcnt(2)
	v_add_f32_e32 v3, v14, v15
	s_waitcnt vmcnt(0)
	v_fmac_f32_e32 v2, v16, v3
	global_store_dword v[0:1], v2, off offset:20
	global_load_dword v2, v83, s[58:59] offset:24
	s_waitcnt lgkmcnt(1)
	v_add_f32_e32 v3, v12, v13
	s_waitcnt vmcnt(0)
	v_fmac_f32_e32 v2, v16, v3
	global_store_dword v[0:1], v2, off offset:24
	global_load_dword v2, v83, s[58:59] offset:28
	s_waitcnt lgkmcnt(0)
	v_add_f32_e32 v3, v10, v11
	s_waitcnt vmcnt(0)
	v_fmac_f32_e32 v2, v16, v3
	global_store_dword v[0:1], v2, off offset:28
